# EpiScale epilogues: 3 more of the 16 output groups per wave deferred into the next tile's K loop, parked in 24 KiB of static LDS above the dynamic LDS
# speedup vs baseline: 1.0055x; 1.0055x over previous
.Lds_P1_a_st:
	s_cmp_eq_u32 s32, 0
	s_cbranch_scc1 .Lds_P1_a_done
	s_cmp_eq_u32 s68, 0
	s_cbranch_scc1 .Lds_P1_a_0
	s_cmp_eq_u32 s68, 2
	s_cbranch_scc1 .Lds_P1_a_1
	s_add_u32 s100, s98, 0x134000
	s_addc_u32 s101, s99, 0
	global_store_dwordx4 v239, v[248:251], s[100:101]
	v_lshrrev_b32_e32 v230, 6, v204
	v_mul_u32_u24_e32 v230, 0xc00, v230
	v_and_b32_e32 v231, 63, v204
	v_lshl_add_u32 v230, v231, 4, v230
	v_add_u32_e32 v230, 0x21010, v230
	ds_read_b128 v[230:233], v230 offset:0
	s_waitcnt lgkmcnt(0)
	s_add_u32 s100, s98, 0xe0000
	s_addc_u32 s101, s99, 0
	global_store_dwordx4 v239, v[230:233], s[100:101]
	s_branch .Lds_P1_a_done

.Lds_P1_b_st:
	s_cmp_eq_u32 s32, 0
	s_cbranch_scc1 .Lds_P1_b_done
	s_cmp_eq_u32 s68, 0
	s_cbranch_scc1 .Lds_P1_b_0
	s_cmp_eq_u32 s68, 2
	s_cbranch_scc1 .Lds_P1_b_1
	s_add_u32 s100, s98, 0x134000
	s_addc_u32 s101, s99, 0
	global_store_dwordx4 v239, v[252:255], s[100:101] offset:256
	v_lshrrev_b32_e32 v234, 6, v204
	v_mul_u32_u24_e32 v234, 0xc00, v234
	v_and_b32_e32 v235, 63, v204
	v_lshl_add_u32 v234, v235, 4, v234
	v_add_u32_e32 v234, 0x21010, v234
	ds_read_b128 v[234:237], v234 offset:1024
	s_waitcnt lgkmcnt(0)
	s_add_u32 s100, s98, 0xe0000
	s_addc_u32 s101, s99, 0
	global_store_dwordx4 v239, v[234:237], s[100:101] offset:256
	s_branch .Lds_P1_b_done
.Lds_P1_b_l6:
	s_cmp_eq_u32 s32, 0
	s_cbranch_scc1 .Lds_P1_b_done
	v_lshrrev_b32_e32 v248, 6, v204
	v_mul_u32_u24_e32 v248, 0xc00, v248
	v_and_b32_e32 v249, 63, v204
	v_lshl_add_u32 v248, v249, 4, v248
	v_add_u32_e32 v248, 0x21010, v248
	ds_read_b128 v[248:251], v248 offset:2048
	s_waitcnt lgkmcnt(0)
	s_add_u32 s100, s98, 0x54000
	s_addc_u32 s101, s99, 0
	global_store_dwordx4 v239, v[248:251], s[100:101] offset:256
	s_branch .Lds_P1_b_done

.Lepi_P1_start:
	s_mul_i32 s82, s6, 0x1c0000
	s_lshl_b32 s84, s64, 9
	s_add_u32 s82, s82, s84
	s_add_u32 s84, s38, s82
	s_addc_u32 s85, s39, 0
	v_pk_mul_f32 v[124:125], v[124:125], v[248:249] op_sel_hi:[1,0]
	v_pk_mul_f32 v[126:127], v[126:127], v[248:249] op_sel_hi:[1,0]
	v_pk_mul_f32 v[120:121], v[120:121], v[248:249] op_sel_hi:[1,0]
	v_pk_mul_f32 v[122:123], v[122:123], v[248:249] op_sel_hi:[1,0]
	v_cvt_pk_bf16_f32 v124, v124, v125
	v_cvt_pk_bf16_f32 v125, v126, v127
	v_cvt_pk_bf16_f32 v126, v120, v121
	v_cvt_pk_bf16_f32 v127, v122, v123
	global_store_dwordx4 v239, v[124:127], s[84:85]
	v_pk_mul_f32 v[112:113], v[112:113], v[248:249] op_sel_hi:[1,0]
	v_pk_mul_f32 v[114:115], v[114:115], v[248:249] op_sel_hi:[1,0]
	v_pk_mul_f32 v[104:105], v[104:105], v[248:249] op_sel_hi:[1,0]
	v_pk_mul_f32 v[106:107], v[106:107], v[248:249] op_sel_hi:[1,0]
	v_cvt_pk_bf16_f32 v112, v112, v113
	v_cvt_pk_bf16_f32 v113, v114, v115
	v_cvt_pk_bf16_f32 v114, v104, v105
	v_cvt_pk_bf16_f32 v115, v106, v107
	global_store_dwordx4 v239, v[112:115], s[84:85] offset:256
	v_pk_mul_f32 v[116:117], v[116:117], v[248:249] op_sel:[0,1] op_sel_hi:[1,1]
	v_pk_mul_f32 v[118:119], v[118:119], v[248:249] op_sel:[0,1] op_sel_hi:[1,1]
	v_pk_mul_f32 v[108:109], v[108:109], v[248:249] op_sel:[0,1] op_sel_hi:[1,1]
	v_pk_mul_f32 v[110:111], v[110:111], v[248:249] op_sel:[0,1] op_sel_hi:[1,1]
	v_cvt_pk_bf16_f32 v116, v116, v117
	v_cvt_pk_bf16_f32 v117, v118, v119
	v_cvt_pk_bf16_f32 v118, v108, v109
	v_cvt_pk_bf16_f32 v119, v110, v111
	s_add_u32 s100, s84, 0x1c000
	s_addc_u32 s101, s85, 0
	global_store_dwordx4 v239, v[116:119], s[100:101]
	v_pk_mul_f32 v[96:97], v[96:97], v[248:249] op_sel:[0,1] op_sel_hi:[1,1]
	v_pk_mul_f32 v[98:99], v[98:99], v[248:249] op_sel:[0,1] op_sel_hi:[1,1]
	v_pk_mul_f32 v[88:89], v[88:89], v[248:249] op_sel:[0,1] op_sel_hi:[1,1]
	v_pk_mul_f32 v[90:91], v[90:91], v[248:249] op_sel:[0,1] op_sel_hi:[1,1]
	v_cvt_pk_bf16_f32 v96, v96, v97
	v_cvt_pk_bf16_f32 v97, v98, v99
	v_cvt_pk_bf16_f32 v98, v88, v89
	v_cvt_pk_bf16_f32 v99, v90, v91
	s_add_u32 s100, s84, 0x1c000
	s_addc_u32 s101, s85, 0
	global_store_dwordx4 v239, v[96:99], s[100:101] offset:256
	v_pk_mul_f32 v[100:101], v[100:101], v[250:251] op_sel_hi:[1,0]
	v_pk_mul_f32 v[102:103], v[102:103], v[250:251] op_sel_hi:[1,0]
	v_pk_mul_f32 v[92:93], v[92:93], v[250:251] op_sel_hi:[1,0]
	v_pk_mul_f32 v[94:95], v[94:95], v[250:251] op_sel_hi:[1,0]
	v_cvt_pk_bf16_f32 v100, v100, v101
	v_cvt_pk_bf16_f32 v101, v102, v103
	v_cvt_pk_bf16_f32 v102, v92, v93
	v_cvt_pk_bf16_f32 v103, v94, v95
	s_add_u32 s100, s84, 0x38000
	s_addc_u32 s101, s85, 0
	global_store_dwordx4 v239, v[100:103], s[100:101]
	v_pk_mul_f32 v[80:81], v[80:81], v[250:251] op_sel_hi:[1,0]
	v_pk_mul_f32 v[82:83], v[82:83], v[250:251] op_sel_hi:[1,0]
	v_pk_mul_f32 v[72:73], v[72:73], v[250:251] op_sel_hi:[1,0]
	v_pk_mul_f32 v[74:75], v[74:75], v[250:251] op_sel_hi:[1,0]
	v_cvt_pk_bf16_f32 v80, v80, v81
	v_cvt_pk_bf16_f32 v81, v82, v83
	v_cvt_pk_bf16_f32 v82, v72, v73
	v_cvt_pk_bf16_f32 v83, v74, v75
	s_add_u32 s100, s84, 0x38000
	s_addc_u32 s101, s85, 0
	global_store_dwordx4 v239, v[80:83], s[100:101] offset:256
	v_pk_mul_f32 v[84:85], v[84:85], v[250:251] op_sel:[0,1] op_sel_hi:[1,1]
	v_pk_mul_f32 v[86:87], v[86:87], v[250:251] op_sel:[0,1] op_sel_hi:[1,1]
	v_pk_mul_f32 v[76:77], v[76:77], v[250:251] op_sel:[0,1] op_sel_hi:[1,1]
	v_pk_mul_f32 v[78:79], v[78:79], v[250:251] op_sel:[0,1] op_sel_hi:[1,1]
	v_cvt_pk_bf16_f32 v84, v84, v85
	v_cvt_pk_bf16_f32 v85, v86, v87
	v_cvt_pk_bf16_f32 v86, v76, v77
	v_cvt_pk_bf16_f32 v87, v78, v79
	s_add_u32 s100, s84, 0x54000
	s_addc_u32 s101, s85, 0
	global_store_dwordx4 v239, v[84:87], s[100:101]
	v_lshrrev_b32_e32 v168, 6, v204
	v_mul_u32_u24_e32 v168, 0xc00, v168
	v_and_b32_e32 v160, 63, v204
	v_lshl_add_u32 v168, v160, 4, v168
	v_add_u32_e32 v168, 0x21010, v168
	v_pk_mul_f32 v[60:61], v[60:61], v[252:253] op_sel_hi:[1,0]
	v_pk_mul_f32 v[62:63], v[62:63], v[252:253] op_sel_hi:[1,0]
	v_pk_mul_f32 v[56:57], v[56:57], v[252:253] op_sel_hi:[1,0]
	v_pk_mul_f32 v[58:59], v[58:59], v[252:253] op_sel_hi:[1,0]
	v_cvt_pk_bf16_f32 v60, v60, v61
	v_cvt_pk_bf16_f32 v61, v62, v63
	v_cvt_pk_bf16_f32 v62, v56, v57
	v_cvt_pk_bf16_f32 v63, v58, v59
	ds_write_b128 v168, v[60:63] offset:0
	v_pk_mul_f32 v[48:49], v[48:49], v[252:253] op_sel_hi:[1,0]
	v_pk_mul_f32 v[50:51], v[50:51], v[252:253] op_sel_hi:[1,0]
	v_pk_mul_f32 v[40:41], v[40:41], v[252:253] op_sel_hi:[1,0]
	v_pk_mul_f32 v[42:43], v[42:43], v[252:253] op_sel_hi:[1,0]
	v_cvt_pk_bf16_f32 v48, v48, v49
	v_cvt_pk_bf16_f32 v49, v50, v51
	v_cvt_pk_bf16_f32 v50, v40, v41
	v_cvt_pk_bf16_f32 v51, v42, v43
	ds_write_b128 v168, v[48:51] offset:1024
	v_pk_mul_f32 v[68:69], v[68:69], v[250:251] op_sel:[0,1] op_sel_hi:[1,1]
	v_pk_mul_f32 v[70:71], v[70:71], v[250:251] op_sel:[0,1] op_sel_hi:[1,1]
	v_pk_mul_f32 v[64:65], v[64:65], v[250:251] op_sel:[0,1] op_sel_hi:[1,1]
	v_pk_mul_f32 v[66:67], v[66:67], v[250:251] op_sel:[0,1] op_sel_hi:[1,1]
	v_cvt_pk_bf16_f32 v68, v68, v69
	v_cvt_pk_bf16_f32 v69, v70, v71
	v_cvt_pk_bf16_f32 v70, v64, v65
	v_cvt_pk_bf16_f32 v71, v66, v67
	ds_write_b128 v168, v[68:71] offset:2048
	v_pk_mul_f32 v[52:53], v[52:53], v[252:253] op_sel:[0,1] op_sel_hi:[1,1]
	v_pk_mul_f32 v[54:55], v[54:55], v[252:253] op_sel:[0,1] op_sel_hi:[1,1]
	v_pk_mul_f32 v[44:45], v[44:45], v[252:253] op_sel:[0,1] op_sel_hi:[1,1]
	v_pk_mul_f32 v[46:47], v[46:47], v[252:253] op_sel:[0,1] op_sel_hi:[1,1]
	v_cvt_pk_bf16_f32 v230, v52, v53
	v_cvt_pk_bf16_f32 v231, v54, v55
	v_cvt_pk_bf16_f32 v232, v44, v45
	v_cvt_pk_bf16_f32 v233, v46, v47
	v_pk_mul_f32 v[32:33], v[32:33], v[252:253] op_sel:[0,1] op_sel_hi:[1,1]
	v_pk_mul_f32 v[34:35], v[34:35], v[252:253] op_sel:[0,1] op_sel_hi:[1,1]
	v_pk_mul_f32 v[24:25], v[24:25], v[252:253] op_sel:[0,1] op_sel_hi:[1,1]
	v_pk_mul_f32 v[26:27], v[26:27], v[252:253] op_sel:[0,1] op_sel_hi:[1,1]
	v_cvt_pk_bf16_f32 v234, v32, v33
	v_cvt_pk_bf16_f32 v235, v34, v35
	v_cvt_pk_bf16_f32 v236, v24, v25
	v_cvt_pk_bf16_f32 v237, v26, v27
	v_pk_mul_f32 v[36:37], v[36:37], v[254:255] op_sel_hi:[1,0]
	v_pk_mul_f32 v[38:39], v[38:39], v[254:255] op_sel_hi:[1,0]
	v_pk_mul_f32 v[28:29], v[28:29], v[254:255] op_sel_hi:[1,0]
	v_pk_mul_f32 v[30:31], v[30:31], v[254:255] op_sel_hi:[1,0]
	v_cvt_pk_bf16_f32 v240, v36, v37
	v_cvt_pk_bf16_f32 v241, v38, v39
	v_cvt_pk_bf16_f32 v242, v28, v29
	v_cvt_pk_bf16_f32 v243, v30, v31
	v_pk_mul_f32 v[16:17], v[16:17], v[254:255] op_sel_hi:[1,0]
	v_pk_mul_f32 v[18:19], v[18:19], v[254:255] op_sel_hi:[1,0]
	v_pk_mul_f32 v[8:9], v[8:9], v[254:255] op_sel_hi:[1,0]
	v_pk_mul_f32 v[10:11], v[10:11], v[254:255] op_sel_hi:[1,0]
	v_cvt_pk_bf16_f32 v244, v16, v17
	v_cvt_pk_bf16_f32 v245, v18, v19
	v_cvt_pk_bf16_f32 v246, v8, v9
	v_cvt_pk_bf16_f32 v247, v10, v11
	v_pk_mul_f32 v[20:21], v[20:21], v[254:255] op_sel:[0,1] op_sel_hi:[1,1]
	v_pk_mul_f32 v[22:23], v[22:23], v[254:255] op_sel:[0,1] op_sel_hi:[1,1]
	v_pk_mul_f32 v[12:13], v[12:13], v[254:255] op_sel:[0,1] op_sel_hi:[1,1]
	v_pk_mul_f32 v[14:15], v[14:15], v[254:255] op_sel:[0,1] op_sel_hi:[1,1]
	v_cvt_pk_bf16_f32 v248, v20, v21
	v_cvt_pk_bf16_f32 v249, v22, v23
	v_cvt_pk_bf16_f32 v250, v12, v13
	v_cvt_pk_bf16_f32 v251, v14, v15
	v_pk_mul_f32 v[4:5], v[4:5], v[254:255] op_sel:[0,1] op_sel_hi:[1,1]
	v_pk_mul_f32 v[6:7], v[6:7], v[254:255] op_sel:[0,1] op_sel_hi:[1,1]
	v_pk_mul_f32 v[0:1], v[0:1], v[254:255] op_sel:[0,1] op_sel_hi:[1,1]
	v_pk_mul_f32 v[2:3], v[2:3], v[254:255] op_sel:[0,1] op_sel_hi:[1,1]
	v_cvt_pk_bf16_f32 v252, v4, v5
	v_cvt_pk_bf16_f32 v253, v6, v7
	v_cvt_pk_bf16_f32 v254, v0, v1
	v_cvt_pk_bf16_f32 v255, v2, v3
	s_mov_b64 s[52:53], s[50:51]
	s_and_b64 vcc, exec, s[4:5]
	s_mov_b32 s64, s42
	s_mov_b32 s6, s44
	s_mov_b64 s[8:9], s[48:49]
	s_mov_b64 s[98:99], s[84:85]
	s_mov_b32 s32, 1
	s_cbranch_vccz .LBB0_156
	s_add_u32 s100, s84, 0xfc000
	s_addc_u32 s101, s85, 0
	global_store_dwordx4 v239, v[230:233], s[100:101]
	s_add_u32 s100, s84, 0xfc000
	s_addc_u32 s101, s85, 0
	global_store_dwordx4 v239, v[234:237], s[100:101] offset:256
	s_add_u32 s100, s84, 0x118000
	s_addc_u32 s101, s85, 0
	global_store_dwordx4 v239, v[240:243], s[100:101]
	s_add_u32 s100, s84, 0x118000
	s_addc_u32 s101, s85, 0
	global_store_dwordx4 v239, v[244:247], s[100:101] offset:256
	s_add_u32 s100, s84, 0x134000
	s_addc_u32 s101, s85, 0
	global_store_dwordx4 v239, v[248:251], s[100:101]
	s_add_u32 s100, s84, 0x134000
	s_addc_u32 s101, s85, 0
	global_store_dwordx4 v239, v[252:255], s[100:101] offset:256
	s_nop 1
	v_lshrrev_b32_e32 v230, 6, v204
	v_mul_u32_u24_e32 v230, 0xc00, v230
	v_and_b32_e32 v231, 63, v204
	v_lshl_add_u32 v230, v231, 4, v230
	v_add_u32_e32 v230, 0x21010, v230
	ds_read_b128 v[230:233], v230 offset:0
	s_waitcnt lgkmcnt(0)
	s_add_u32 s100, s84, 0xe0000
	s_addc_u32 s101, s85, 0
	global_store_dwordx4 v239, v[230:233], s[100:101]
	v_lshrrev_b32_e32 v234, 6, v204
	v_mul_u32_u24_e32 v234, 0xc00, v234
	v_and_b32_e32 v235, 63, v204
	v_lshl_add_u32 v234, v235, 4, v234
	v_add_u32_e32 v234, 0x21010, v234
	ds_read_b128 v[234:237], v234 offset:1024
	s_waitcnt lgkmcnt(0)
	s_add_u32 s100, s84, 0xe0000
	s_addc_u32 s101, s85, 0
	global_store_dwordx4 v239, v[234:237], s[100:101] offset:256
	v_lshrrev_b32_e32 v248, 6, v204
	v_mul_u32_u24_e32 v248, 0xc00, v248
	v_and_b32_e32 v249, 63, v204
	v_lshl_add_u32 v248, v249, 4, v248
	v_add_u32_e32 v248, 0x21010, v248
	ds_read_b128 v[248:251], v248 offset:2048
	s_waitcnt lgkmcnt(0)
	s_add_u32 s100, s84, 0x54000
	s_addc_u32 s101, s85, 0
	global_store_dwordx4 v239, v[248:251], s[100:101] offset:256
	s_waitcnt vmcnt(0)
	s_cmpk_gt_u32 s0, 0xff
	s_cbranch_scc1 .LBB0_163
	s_barrier

.Lds_P6_a_st:
	s_cmp_eq_u32 s32, 0
	s_cbranch_scc1 .Lds_P6_a_done
	s_cmp_eq_u32 s71, 0
	s_cbranch_scc1 .Lds_P6_a_0
	s_cmp_eq_u32 s71, 2
	s_cbranch_scc1 .Lds_P6_a_1
	s_add_u32 s100, s98, 0x160000
	s_addc_u32 s101, s99, 0
	global_store_dwordx4 v239, v[248:251], s[100:101]
	v_lshrrev_b32_e32 v230, 6, v204
	v_mul_u32_u24_e32 v230, 0xc00, v230
	v_and_b32_e32 v231, 63, v204
	v_lshl_add_u32 v230, v231, 4, v230
	v_add_u32_e32 v230, 0x21010, v230
	ds_read_b128 v[230:233], v230 offset:0
	s_waitcnt lgkmcnt(0)
	s_add_u32 s100, s98, 0x100000
	s_addc_u32 s101, s99, 0
	global_store_dwordx4 v239, v[230:233], s[100:101]
	s_branch .Lds_P6_a_done

.Lds_P6_b_st:
	s_cmp_eq_u32 s32, 0
	s_cbranch_scc1 .Lds_P6_b_done
	s_cmp_eq_u32 s71, 0
	s_cbranch_scc1 .Lds_P6_b_0
	s_cmp_eq_u32 s71, 2
	s_cbranch_scc1 .Lds_P6_b_1
	s_add_u32 s100, s98, 0x160000
	s_addc_u32 s101, s99, 0
	global_store_dwordx4 v239, v[252:255], s[100:101] offset:256
	v_lshrrev_b32_e32 v234, 6, v204
	v_mul_u32_u24_e32 v234, 0xc00, v234
	v_and_b32_e32 v235, 63, v204
	v_lshl_add_u32 v234, v235, 4, v234
	v_add_u32_e32 v234, 0x21010, v234
	ds_read_b128 v[234:237], v234 offset:1024
	s_waitcnt lgkmcnt(0)
	s_add_u32 s100, s98, 0x100000
	s_addc_u32 s101, s99, 0
	global_store_dwordx4 v239, v[234:237], s[100:101] offset:256
	s_branch .Lds_P6_b_done
.Lds_P6_b_l6:
	s_cmp_eq_u32 s32, 0
	s_cbranch_scc1 .Lds_P6_b_done
	v_lshrrev_b32_e32 v248, 6, v204
	v_mul_u32_u24_e32 v248, 0xc00, v248
	v_and_b32_e32 v249, 63, v204
	v_lshl_add_u32 v248, v249, 4, v248
	v_add_u32_e32 v248, 0x21010, v248
	ds_read_b128 v[248:251], v248 offset:2048
	s_waitcnt lgkmcnt(0)
	s_add_u32 s100, s98, 0x60000
	s_addc_u32 s101, s99, 0
	global_store_dwordx4 v239, v[248:251], s[100:101] offset:256
	s_branch .Lds_P6_b_done

.Lepi_P6_start:
	s_mul_i32 s82, s10, 0x200000
	s_lshl_b32 s84, s67, 9
	s_add_u32 s82, s82, s84
	s_add_u32 s84, s16, s82
	s_addc_u32 s85, s17, 0
	v_pk_mul_f32 v[124:125], v[124:125], v[248:249] op_sel_hi:[1,0]
	v_pk_mul_f32 v[126:127], v[126:127], v[248:249] op_sel_hi:[1,0]
	v_pk_mul_f32 v[120:121], v[120:121], v[248:249] op_sel_hi:[1,0]
	v_pk_mul_f32 v[122:123], v[122:123], v[248:249] op_sel_hi:[1,0]
	v_max_f32_e32 v124, 0, v124
	v_max_f32_e32 v125, 0, v125
	v_max_f32_e32 v126, 0, v126
	v_max_f32_e32 v127, 0, v127
	v_max_f32_e32 v120, 0, v120
	v_max_f32_e32 v121, 0, v121
	v_max_f32_e32 v122, 0, v122
	v_max_f32_e32 v123, 0, v123
	v_pk_mul_f32 v[124:125], v[124:125], v[124:125]
	v_pk_mul_f32 v[126:127], v[126:127], v[126:127]
	v_pk_mul_f32 v[120:121], v[120:121], v[120:121]
	v_pk_mul_f32 v[122:123], v[122:123], v[122:123]
	v_cvt_pk_bf16_f32 v124, v124, v125
	v_cvt_pk_bf16_f32 v125, v126, v127
	v_cvt_pk_bf16_f32 v126, v120, v121
	v_cvt_pk_bf16_f32 v127, v122, v123
	global_store_dwordx4 v239, v[124:127], s[84:85]
	v_pk_mul_f32 v[116:117], v[116:117], v[248:249] op_sel_hi:[1,0]
	v_pk_mul_f32 v[118:119], v[118:119], v[248:249] op_sel_hi:[1,0]
	v_pk_mul_f32 v[112:113], v[112:113], v[248:249] op_sel_hi:[1,0]
	v_pk_mul_f32 v[114:115], v[114:115], v[248:249] op_sel_hi:[1,0]
	v_max_f32_e32 v116, 0, v116
	v_max_f32_e32 v117, 0, v117
	v_max_f32_e32 v118, 0, v118
	v_max_f32_e32 v119, 0, v119
	v_max_f32_e32 v112, 0, v112
	v_max_f32_e32 v113, 0, v113
	v_max_f32_e32 v114, 0, v114
	v_max_f32_e32 v115, 0, v115
	v_pk_mul_f32 v[116:117], v[116:117], v[116:117]
	v_pk_mul_f32 v[118:119], v[118:119], v[118:119]
	v_pk_mul_f32 v[112:113], v[112:113], v[112:113]
	v_pk_mul_f32 v[114:115], v[114:115], v[114:115]
	v_cvt_pk_bf16_f32 v116, v116, v117
	v_cvt_pk_bf16_f32 v117, v118, v119
	v_cvt_pk_bf16_f32 v118, v112, v113
	v_cvt_pk_bf16_f32 v119, v114, v115
	global_store_dwordx4 v239, v[116:119], s[84:85] offset:256
	v_pk_mul_f32 v[108:109], v[108:109], v[248:249] op_sel:[0,1] op_sel_hi:[1,1]
	v_pk_mul_f32 v[110:111], v[110:111], v[248:249] op_sel:[0,1] op_sel_hi:[1,1]
	v_pk_mul_f32 v[104:105], v[104:105], v[248:249] op_sel:[0,1] op_sel_hi:[1,1]
	v_pk_mul_f32 v[106:107], v[106:107], v[248:249] op_sel:[0,1] op_sel_hi:[1,1]
	v_max_f32_e32 v108, 0, v108
	v_max_f32_e32 v109, 0, v109
	v_max_f32_e32 v110, 0, v110
	v_max_f32_e32 v111, 0, v111
	v_max_f32_e32 v104, 0, v104
	v_max_f32_e32 v105, 0, v105
	v_max_f32_e32 v106, 0, v106
	v_max_f32_e32 v107, 0, v107
	v_pk_mul_f32 v[108:109], v[108:109], v[108:109]
	v_pk_mul_f32 v[110:111], v[110:111], v[110:111]
	v_pk_mul_f32 v[104:105], v[104:105], v[104:105]
	v_pk_mul_f32 v[106:107], v[106:107], v[106:107]
	v_cvt_pk_bf16_f32 v108, v108, v109
	v_cvt_pk_bf16_f32 v109, v110, v111
	v_cvt_pk_bf16_f32 v110, v104, v105
	v_cvt_pk_bf16_f32 v111, v106, v107
	s_add_u32 s100, s84, 0x20000
	s_addc_u32 s101, s85, 0
	global_store_dwordx4 v239, v[108:111], s[100:101]
	v_pk_mul_f32 v[100:101], v[100:101], v[248:249] op_sel:[0,1] op_sel_hi:[1,1]
	v_pk_mul_f32 v[102:103], v[102:103], v[248:249] op_sel:[0,1] op_sel_hi:[1,1]
	v_pk_mul_f32 v[96:97], v[96:97], v[248:249] op_sel:[0,1] op_sel_hi:[1,1]
	v_pk_mul_f32 v[98:99], v[98:99], v[248:249] op_sel:[0,1] op_sel_hi:[1,1]
	v_max_f32_e32 v100, 0, v100
	v_max_f32_e32 v101, 0, v101
	v_max_f32_e32 v102, 0, v102
	v_max_f32_e32 v103, 0, v103
	v_max_f32_e32 v96, 0, v96
	v_max_f32_e32 v97, 0, v97
	v_max_f32_e32 v98, 0, v98
	v_max_f32_e32 v99, 0, v99
	v_pk_mul_f32 v[100:101], v[100:101], v[100:101]
	v_pk_mul_f32 v[102:103], v[102:103], v[102:103]
	v_pk_mul_f32 v[96:97], v[96:97], v[96:97]
	v_pk_mul_f32 v[98:99], v[98:99], v[98:99]
	v_cvt_pk_bf16_f32 v100, v100, v101
	v_cvt_pk_bf16_f32 v101, v102, v103
	v_cvt_pk_bf16_f32 v102, v96, v97
	v_cvt_pk_bf16_f32 v103, v98, v99
	s_add_u32 s100, s84, 0x20000
	s_addc_u32 s101, s85, 0
	global_store_dwordx4 v239, v[100:103], s[100:101] offset:256
	v_pk_mul_f32 v[92:93], v[92:93], v[250:251] op_sel_hi:[1,0]
	v_pk_mul_f32 v[94:95], v[94:95], v[250:251] op_sel_hi:[1,0]
	v_pk_mul_f32 v[88:89], v[88:89], v[250:251] op_sel_hi:[1,0]
	v_pk_mul_f32 v[90:91], v[90:91], v[250:251] op_sel_hi:[1,0]
	v_max_f32_e32 v92, 0, v92
	v_max_f32_e32 v93, 0, v93
	v_max_f32_e32 v94, 0, v94
	v_max_f32_e32 v95, 0, v95
	v_max_f32_e32 v88, 0, v88
	v_max_f32_e32 v89, 0, v89
	v_max_f32_e32 v90, 0, v90
	v_max_f32_e32 v91, 0, v91
	v_pk_mul_f32 v[92:93], v[92:93], v[92:93]
	v_pk_mul_f32 v[94:95], v[94:95], v[94:95]
	v_pk_mul_f32 v[88:89], v[88:89], v[88:89]
	v_pk_mul_f32 v[90:91], v[90:91], v[90:91]
	v_cvt_pk_bf16_f32 v92, v92, v93
	v_cvt_pk_bf16_f32 v93, v94, v95
	v_cvt_pk_bf16_f32 v94, v88, v89
	v_cvt_pk_bf16_f32 v95, v90, v91
	s_add_u32 s100, s84, 0x40000
	s_addc_u32 s101, s85, 0
	global_store_dwordx4 v239, v[92:95], s[100:101]
	v_pk_mul_f32 v[84:85], v[84:85], v[250:251] op_sel_hi:[1,0]
	v_pk_mul_f32 v[86:87], v[86:87], v[250:251] op_sel_hi:[1,0]
	v_pk_mul_f32 v[80:81], v[80:81], v[250:251] op_sel_hi:[1,0]
	v_pk_mul_f32 v[82:83], v[82:83], v[250:251] op_sel_hi:[1,0]
	v_max_f32_e32 v84, 0, v84
	v_max_f32_e32 v85, 0, v85
	v_max_f32_e32 v86, 0, v86
	v_max_f32_e32 v87, 0, v87
	v_max_f32_e32 v80, 0, v80
	v_max_f32_e32 v81, 0, v81
	v_max_f32_e32 v82, 0, v82
	v_max_f32_e32 v83, 0, v83
	v_pk_mul_f32 v[84:85], v[84:85], v[84:85]
	v_pk_mul_f32 v[86:87], v[86:87], v[86:87]
	v_pk_mul_f32 v[80:81], v[80:81], v[80:81]
	v_pk_mul_f32 v[82:83], v[82:83], v[82:83]
	v_cvt_pk_bf16_f32 v84, v84, v85
	v_cvt_pk_bf16_f32 v85, v86, v87
	v_cvt_pk_bf16_f32 v86, v80, v81
	v_cvt_pk_bf16_f32 v87, v82, v83
	s_add_u32 s100, s84, 0x40000
	s_addc_u32 s101, s85, 0
	global_store_dwordx4 v239, v[84:87], s[100:101] offset:256
	v_pk_mul_f32 v[76:77], v[76:77], v[250:251] op_sel:[0,1] op_sel_hi:[1,1]
	v_pk_mul_f32 v[78:79], v[78:79], v[250:251] op_sel:[0,1] op_sel_hi:[1,1]
	v_pk_mul_f32 v[72:73], v[72:73], v[250:251] op_sel:[0,1] op_sel_hi:[1,1]
	v_pk_mul_f32 v[74:75], v[74:75], v[250:251] op_sel:[0,1] op_sel_hi:[1,1]
	v_max_f32_e32 v76, 0, v76
	v_max_f32_e32 v77, 0, v77
	v_max_f32_e32 v78, 0, v78
	v_max_f32_e32 v79, 0, v79
	v_max_f32_e32 v72, 0, v72
	v_max_f32_e32 v73, 0, v73
	v_max_f32_e32 v74, 0, v74
	v_max_f32_e32 v75, 0, v75
	v_pk_mul_f32 v[76:77], v[76:77], v[76:77]
	v_pk_mul_f32 v[78:79], v[78:79], v[78:79]
	v_pk_mul_f32 v[72:73], v[72:73], v[72:73]
	v_pk_mul_f32 v[74:75], v[74:75], v[74:75]
	v_cvt_pk_bf16_f32 v76, v76, v77
	v_cvt_pk_bf16_f32 v77, v78, v79
	v_cvt_pk_bf16_f32 v78, v72, v73
	v_cvt_pk_bf16_f32 v79, v74, v75
	s_add_u32 s100, s84, 0x60000
	s_addc_u32 s101, s85, 0
	global_store_dwordx4 v239, v[76:79], s[100:101]
	v_lshrrev_b32_e32 v144, 6, v204
	v_mul_u32_u24_e32 v144, 0xc00, v144
	v_and_b32_e32 v172, 63, v204
	v_lshl_add_u32 v144, v172, 4, v144
	v_add_u32_e32 v144, 0x21010, v144
	v_pk_mul_f32 v[60:61], v[60:61], v[252:253] op_sel_hi:[1,0]
	v_pk_mul_f32 v[62:63], v[62:63], v[252:253] op_sel_hi:[1,0]
	v_pk_mul_f32 v[56:57], v[56:57], v[252:253] op_sel_hi:[1,0]
	v_pk_mul_f32 v[58:59], v[58:59], v[252:253] op_sel_hi:[1,0]
	v_max_f32_e32 v60, 0, v60
	v_max_f32_e32 v61, 0, v61
	v_max_f32_e32 v62, 0, v62
	v_max_f32_e32 v63, 0, v63
	v_max_f32_e32 v56, 0, v56
	v_max_f32_e32 v57, 0, v57
	v_max_f32_e32 v58, 0, v58
	v_max_f32_e32 v59, 0, v59
	v_pk_mul_f32 v[60:61], v[60:61], v[60:61]
	v_pk_mul_f32 v[62:63], v[62:63], v[62:63]
	v_pk_mul_f32 v[56:57], v[56:57], v[56:57]
	v_pk_mul_f32 v[58:59], v[58:59], v[58:59]
	v_cvt_pk_bf16_f32 v60, v60, v61
	v_cvt_pk_bf16_f32 v61, v62, v63
	v_cvt_pk_bf16_f32 v62, v56, v57
	v_cvt_pk_bf16_f32 v63, v58, v59
	ds_write_b128 v144, v[60:63] offset:0
	v_pk_mul_f32 v[52:53], v[52:53], v[252:253] op_sel_hi:[1,0]
	v_pk_mul_f32 v[54:55], v[54:55], v[252:253] op_sel_hi:[1,0]
	v_pk_mul_f32 v[48:49], v[48:49], v[252:253] op_sel_hi:[1,0]
	v_pk_mul_f32 v[50:51], v[50:51], v[252:253] op_sel_hi:[1,0]
	v_max_f32_e32 v52, 0, v52
	v_max_f32_e32 v53, 0, v53
	v_max_f32_e32 v54, 0, v54
	v_max_f32_e32 v55, 0, v55
	v_max_f32_e32 v48, 0, v48
	v_max_f32_e32 v49, 0, v49
	v_max_f32_e32 v50, 0, v50
	v_max_f32_e32 v51, 0, v51
	v_pk_mul_f32 v[52:53], v[52:53], v[52:53]
	v_pk_mul_f32 v[54:55], v[54:55], v[54:55]
	v_pk_mul_f32 v[48:49], v[48:49], v[48:49]
	v_pk_mul_f32 v[50:51], v[50:51], v[50:51]
	v_cvt_pk_bf16_f32 v52, v52, v53
	v_cvt_pk_bf16_f32 v53, v54, v55
	v_cvt_pk_bf16_f32 v54, v48, v49
	v_cvt_pk_bf16_f32 v55, v50, v51
	ds_write_b128 v144, v[52:55] offset:1024
	v_pk_mul_f32 v[68:69], v[68:69], v[250:251] op_sel:[0,1] op_sel_hi:[1,1]
	v_pk_mul_f32 v[70:71], v[70:71], v[250:251] op_sel:[0,1] op_sel_hi:[1,1]
	v_pk_mul_f32 v[64:65], v[64:65], v[250:251] op_sel:[0,1] op_sel_hi:[1,1]
	v_pk_mul_f32 v[66:67], v[66:67], v[250:251] op_sel:[0,1] op_sel_hi:[1,1]
	v_max_f32_e32 v68, 0, v68
	v_max_f32_e32 v69, 0, v69
	v_max_f32_e32 v70, 0, v70
	v_max_f32_e32 v71, 0, v71
	v_max_f32_e32 v64, 0, v64
	v_max_f32_e32 v65, 0, v65
	v_max_f32_e32 v66, 0, v66
	v_max_f32_e32 v67, 0, v67
	v_pk_mul_f32 v[68:69], v[68:69], v[68:69]
	v_pk_mul_f32 v[70:71], v[70:71], v[70:71]
	v_pk_mul_f32 v[64:65], v[64:65], v[64:65]
	v_pk_mul_f32 v[66:67], v[66:67], v[66:67]
	v_cvt_pk_bf16_f32 v68, v68, v69
	v_cvt_pk_bf16_f32 v69, v70, v71
	v_cvt_pk_bf16_f32 v70, v64, v65
	v_cvt_pk_bf16_f32 v71, v66, v67
	ds_write_b128 v144, v[68:71] offset:2048
	v_pk_mul_f32 v[44:45], v[44:45], v[252:253] op_sel:[0,1] op_sel_hi:[1,1]
	v_pk_mul_f32 v[46:47], v[46:47], v[252:253] op_sel:[0,1] op_sel_hi:[1,1]
	v_pk_mul_f32 v[40:41], v[40:41], v[252:253] op_sel:[0,1] op_sel_hi:[1,1]
	v_pk_mul_f32 v[42:43], v[42:43], v[252:253] op_sel:[0,1] op_sel_hi:[1,1]
	v_max_f32_e32 v44, 0, v44
	v_max_f32_e32 v45, 0, v45
	v_max_f32_e32 v46, 0, v46
	v_max_f32_e32 v47, 0, v47
	v_max_f32_e32 v40, 0, v40
	v_max_f32_e32 v41, 0, v41
	v_max_f32_e32 v42, 0, v42
	v_max_f32_e32 v43, 0, v43
	v_pk_mul_f32 v[44:45], v[44:45], v[44:45]
	v_pk_mul_f32 v[46:47], v[46:47], v[46:47]
	v_pk_mul_f32 v[40:41], v[40:41], v[40:41]
	v_pk_mul_f32 v[42:43], v[42:43], v[42:43]
	v_cvt_pk_bf16_f32 v230, v44, v45
	v_cvt_pk_bf16_f32 v231, v46, v47
	v_cvt_pk_bf16_f32 v232, v40, v41
	v_cvt_pk_bf16_f32 v233, v42, v43
	v_pk_mul_f32 v[36:37], v[36:37], v[252:253] op_sel:[0,1] op_sel_hi:[1,1]
	v_pk_mul_f32 v[38:39], v[38:39], v[252:253] op_sel:[0,1] op_sel_hi:[1,1]
	v_pk_mul_f32 v[32:33], v[32:33], v[252:253] op_sel:[0,1] op_sel_hi:[1,1]
	v_pk_mul_f32 v[34:35], v[34:35], v[252:253] op_sel:[0,1] op_sel_hi:[1,1]
	v_max_f32_e32 v36, 0, v36
	v_max_f32_e32 v37, 0, v37
	v_max_f32_e32 v38, 0, v38
	v_max_f32_e32 v39, 0, v39
	v_max_f32_e32 v32, 0, v32
	v_max_f32_e32 v33, 0, v33
	v_max_f32_e32 v34, 0, v34
	v_max_f32_e32 v35, 0, v35
	v_pk_mul_f32 v[36:37], v[36:37], v[36:37]
	v_pk_mul_f32 v[38:39], v[38:39], v[38:39]
	v_pk_mul_f32 v[32:33], v[32:33], v[32:33]
	v_pk_mul_f32 v[34:35], v[34:35], v[34:35]
	v_cvt_pk_bf16_f32 v234, v36, v37
	v_cvt_pk_bf16_f32 v235, v38, v39
	v_cvt_pk_bf16_f32 v236, v32, v33
	v_cvt_pk_bf16_f32 v237, v34, v35
	v_pk_mul_f32 v[28:29], v[28:29], v[254:255] op_sel_hi:[1,0]
	v_pk_mul_f32 v[30:31], v[30:31], v[254:255] op_sel_hi:[1,0]
	v_pk_mul_f32 v[24:25], v[24:25], v[254:255] op_sel_hi:[1,0]
	v_pk_mul_f32 v[26:27], v[26:27], v[254:255] op_sel_hi:[1,0]
	v_max_f32_e32 v28, 0, v28
	v_max_f32_e32 v29, 0, v29
	v_max_f32_e32 v30, 0, v30
	v_max_f32_e32 v31, 0, v31
	v_max_f32_e32 v24, 0, v24
	v_max_f32_e32 v25, 0, v25
	v_max_f32_e32 v26, 0, v26
	v_max_f32_e32 v27, 0, v27
	v_pk_mul_f32 v[28:29], v[28:29], v[28:29]
	v_pk_mul_f32 v[30:31], v[30:31], v[30:31]
	v_pk_mul_f32 v[24:25], v[24:25], v[24:25]
	v_pk_mul_f32 v[26:27], v[26:27], v[26:27]
	v_cvt_pk_bf16_f32 v240, v28, v29
	v_cvt_pk_bf16_f32 v241, v30, v31
	v_cvt_pk_bf16_f32 v242, v24, v25
	v_cvt_pk_bf16_f32 v243, v26, v27
	v_pk_mul_f32 v[20:21], v[20:21], v[254:255] op_sel_hi:[1,0]
	v_pk_mul_f32 v[22:23], v[22:23], v[254:255] op_sel_hi:[1,0]
	v_pk_mul_f32 v[16:17], v[16:17], v[254:255] op_sel_hi:[1,0]
	v_pk_mul_f32 v[18:19], v[18:19], v[254:255] op_sel_hi:[1,0]
	v_max_f32_e32 v20, 0, v20
	v_max_f32_e32 v21, 0, v21
	v_max_f32_e32 v22, 0, v22
	v_max_f32_e32 v23, 0, v23
	v_max_f32_e32 v16, 0, v16
	v_max_f32_e32 v17, 0, v17
	v_max_f32_e32 v18, 0, v18
	v_max_f32_e32 v19, 0, v19
	v_pk_mul_f32 v[20:21], v[20:21], v[20:21]
	v_pk_mul_f32 v[22:23], v[22:23], v[22:23]
	v_pk_mul_f32 v[16:17], v[16:17], v[16:17]
	v_pk_mul_f32 v[18:19], v[18:19], v[18:19]
	v_cvt_pk_bf16_f32 v244, v20, v21
	v_cvt_pk_bf16_f32 v245, v22, v23
	v_cvt_pk_bf16_f32 v246, v16, v17
	v_cvt_pk_bf16_f32 v247, v18, v19
	v_pk_mul_f32 v[12:13], v[12:13], v[254:255] op_sel:[0,1] op_sel_hi:[1,1]
	v_pk_mul_f32 v[14:15], v[14:15], v[254:255] op_sel:[0,1] op_sel_hi:[1,1]
	v_pk_mul_f32 v[8:9], v[8:9], v[254:255] op_sel:[0,1] op_sel_hi:[1,1]
	v_pk_mul_f32 v[10:11], v[10:11], v[254:255] op_sel:[0,1] op_sel_hi:[1,1]
	v_max_f32_e32 v12, 0, v12
	v_max_f32_e32 v13, 0, v13
	v_max_f32_e32 v14, 0, v14
	v_max_f32_e32 v15, 0, v15
	v_max_f32_e32 v8, 0, v8
	v_max_f32_e32 v9, 0, v9
	v_max_f32_e32 v10, 0, v10
	v_max_f32_e32 v11, 0, v11
	v_pk_mul_f32 v[12:13], v[12:13], v[12:13]
	v_pk_mul_f32 v[14:15], v[14:15], v[14:15]
	v_pk_mul_f32 v[8:9], v[8:9], v[8:9]
	v_pk_mul_f32 v[10:11], v[10:11], v[10:11]
	v_cvt_pk_bf16_f32 v248, v12, v13
	v_cvt_pk_bf16_f32 v249, v14, v15
	v_cvt_pk_bf16_f32 v250, v8, v9
	v_cvt_pk_bf16_f32 v251, v10, v11
	v_pk_mul_f32 v[4:5], v[4:5], v[254:255] op_sel:[0,1] op_sel_hi:[1,1]
	v_pk_mul_f32 v[6:7], v[6:7], v[254:255] op_sel:[0,1] op_sel_hi:[1,1]
	v_pk_mul_f32 v[0:1], v[0:1], v[254:255] op_sel:[0,1] op_sel_hi:[1,1]
	v_pk_mul_f32 v[2:3], v[2:3], v[254:255] op_sel:[0,1] op_sel_hi:[1,1]
	v_max_f32_e32 v4, 0, v4
	v_max_f32_e32 v5, 0, v5
	v_max_f32_e32 v6, 0, v6
	v_max_f32_e32 v7, 0, v7
	v_max_f32_e32 v0, 0, v0
	v_max_f32_e32 v1, 0, v1
	v_max_f32_e32 v2, 0, v2
	v_max_f32_e32 v3, 0, v3
	v_pk_mul_f32 v[4:5], v[4:5], v[4:5]
	v_pk_mul_f32 v[6:7], v[6:7], v[6:7]
	v_pk_mul_f32 v[0:1], v[0:1], v[0:1]
	v_pk_mul_f32 v[2:3], v[2:3], v[2:3]
	v_cvt_pk_bf16_f32 v252, v4, v5
	v_cvt_pk_bf16_f32 v253, v6, v7
	v_cvt_pk_bf16_f32 v254, v0, v1
	v_cvt_pk_bf16_f32 v255, v2, v3
	s_mov_b64 s[56:57], s[54:55]
	s_and_b64 vcc, exec, s[8:9]
	s_mov_b32 s67, s38
	s_mov_b32 s10, s50
	s_mov_b64 s[12:13], s[52:53]
	s_mov_b64 s[98:99], s[84:85]
	s_mov_b32 s32, 1
	s_cbranch_vccz .LBB0_980
	s_add_u32 s100, s84, 0x120000
	s_addc_u32 s101, s85, 0
	global_store_dwordx4 v239, v[230:233], s[100:101]
	s_add_u32 s100, s84, 0x120000
	s_addc_u32 s101, s85, 0
	global_store_dwordx4 v239, v[234:237], s[100:101] offset:256
	s_add_u32 s100, s84, 0x140000
	s_addc_u32 s101, s85, 0
	global_store_dwordx4 v239, v[240:243], s[100:101]
	s_add_u32 s100, s84, 0x140000
	s_addc_u32 s101, s85, 0
	global_store_dwordx4 v239, v[244:247], s[100:101] offset:256
	s_add_u32 s100, s84, 0x160000
	s_addc_u32 s101, s85, 0
	global_store_dwordx4 v239, v[248:251], s[100:101]
	s_add_u32 s100, s84, 0x160000
	s_addc_u32 s101, s85, 0
	global_store_dwordx4 v239, v[252:255], s[100:101] offset:256
	s_nop 1
	v_lshrrev_b32_e32 v230, 6, v204
	v_mul_u32_u24_e32 v230, 0xc00, v230
	v_and_b32_e32 v231, 63, v204
	v_lshl_add_u32 v230, v231, 4, v230
	v_add_u32_e32 v230, 0x21010, v230
	ds_read_b128 v[230:233], v230 offset:0
	s_waitcnt lgkmcnt(0)
	s_add_u32 s100, s84, 0x100000
	s_addc_u32 s101, s85, 0
	global_store_dwordx4 v239, v[230:233], s[100:101]
	v_lshrrev_b32_e32 v234, 6, v204
	v_mul_u32_u24_e32 v234, 0xc00, v234
	v_and_b32_e32 v235, 63, v204
	v_lshl_add_u32 v234, v235, 4, v234
	v_add_u32_e32 v234, 0x21010, v234
	ds_read_b128 v[234:237], v234 offset:1024
	s_waitcnt lgkmcnt(0)
	s_add_u32 s100, s84, 0x100000
	s_addc_u32 s101, s85, 0
	global_store_dwordx4 v239, v[234:237], s[100:101] offset:256
	v_lshrrev_b32_e32 v248, 6, v204
	v_mul_u32_u24_e32 v248, 0xc00, v248
	v_and_b32_e32 v249, 63, v204
	v_lshl_add_u32 v248, v249, 4, v248
	v_add_u32_e32 v248, 0x21010, v248
	ds_read_b128 v[248:251], v248 offset:2048
	s_waitcnt lgkmcnt(0)
	s_add_u32 s100, s84, 0x60000
	s_addc_u32 s101, s85, 0
	global_store_dwordx4 v239, v[248:251], s[100:101] offset:256
	s_waitcnt vmcnt(0)
	s_cmpk_gt_u32 s0, 0xff
	s_cbranch_scc1 .LBB0_991
	s_barrier

.Lds_P8_a_st:
	s_cmp_eq_u32 s32, 0
	s_cbranch_scc1 .Lds_P8_a_done
	s_cmp_eq_u32 s77, 0
	s_cbranch_scc1 .Lds_P8_a_0
	s_cmp_eq_u32 s77, 2
	s_cbranch_scc1 .Lds_P8_a_1
	s_add_u32 s100, s98, 0x11e000
	s_addc_u32 s101, s99, 0
	global_store_dwordx4 v239, v[248:251], s[100:101]
	v_lshrrev_b32_e32 v230, 6, v204
	v_mul_u32_u24_e32 v230, 0xc00, v230
	v_and_b32_e32 v231, 63, v204
	v_lshl_add_u32 v230, v231, 4, v230
	v_add_u32_e32 v230, 0x21010, v230
	ds_read_b128 v[230:233], v230 offset:0
	s_waitcnt lgkmcnt(0)
	s_add_u32 s100, s98, 0xd0000
	s_addc_u32 s101, s99, 0
	global_store_dwordx4 v239, v[230:233], s[100:101]
	s_branch .Lds_P8_a_done

.Lds_P8_b_st:
	s_cmp_eq_u32 s32, 0
	s_cbranch_scc1 .Lds_P8_b_done
	s_cmp_eq_u32 s77, 0
	s_cbranch_scc1 .Lds_P8_b_0
	s_cmp_eq_u32 s77, 2
	s_cbranch_scc1 .Lds_P8_b_1
	s_add_u32 s100, s98, 0x11e000
	s_addc_u32 s101, s99, 0
	global_store_dwordx4 v239, v[252:255], s[100:101] offset:256
	v_lshrrev_b32_e32 v234, 6, v204
	v_mul_u32_u24_e32 v234, 0xc00, v234
	v_and_b32_e32 v235, 63, v204
	v_lshl_add_u32 v234, v235, 4, v234
	v_add_u32_e32 v234, 0x21010, v234
	ds_read_b128 v[234:237], v234 offset:1024
	s_waitcnt lgkmcnt(0)
	s_add_u32 s100, s98, 0xd0000
	s_addc_u32 s101, s99, 0
	global_store_dwordx4 v239, v[234:237], s[100:101] offset:256
	s_branch .Lds_P8_b_done
.Lds_P8_b_l6:
	s_cmp_eq_u32 s32, 0
	s_cbranch_scc1 .Lds_P8_b_done
	v_lshrrev_b32_e32 v248, 6, v204
	v_mul_u32_u24_e32 v248, 0xc00, v248
	v_and_b32_e32 v249, 63, v204
	v_lshl_add_u32 v248, v249, 4, v248
	v_add_u32_e32 v248, 0x21010, v248
	ds_read_b128 v[248:251], v248 offset:2048
	s_waitcnt lgkmcnt(0)
	s_add_u32 s100, s98, 0x4e000
	s_addc_u32 s101, s99, 0
	global_store_dwordx4 v239, v[248:251], s[100:101] offset:256
	s_branch .Lds_P8_b_done

.Lepi_P8_start:
	s_mul_i32 s82, s10, 0x1a0000
	s_lshl_b32 s84, s73, 9
	s_add_u32 s82, s82, s84
	s_add_u32 s84, s52, s82
	s_addc_u32 s85, s53, 0
	v_pk_mul_f32 v[124:125], v[124:125], v[248:249] op_sel_hi:[1,0]
	v_pk_mul_f32 v[126:127], v[126:127], v[248:249] op_sel_hi:[1,0]
	v_pk_mul_f32 v[120:121], v[120:121], v[248:249] op_sel_hi:[1,0]
	v_pk_mul_f32 v[122:123], v[122:123], v[248:249] op_sel_hi:[1,0]
	v_cvt_pk_bf16_f32 v124, v124, v125
	v_cvt_pk_bf16_f32 v125, v126, v127
	v_cvt_pk_bf16_f32 v126, v120, v121
	v_cvt_pk_bf16_f32 v127, v122, v123
	global_store_dwordx4 v239, v[124:127], s[84:85]
	v_pk_mul_f32 v[112:113], v[112:113], v[248:249] op_sel_hi:[1,0]
	v_pk_mul_f32 v[114:115], v[114:115], v[248:249] op_sel_hi:[1,0]
	v_pk_mul_f32 v[104:105], v[104:105], v[248:249] op_sel_hi:[1,0]
	v_pk_mul_f32 v[106:107], v[106:107], v[248:249] op_sel_hi:[1,0]
	v_cvt_pk_bf16_f32 v112, v112, v113
	v_cvt_pk_bf16_f32 v113, v114, v115
	v_cvt_pk_bf16_f32 v114, v104, v105
	v_cvt_pk_bf16_f32 v115, v106, v107
	global_store_dwordx4 v239, v[112:115], s[84:85] offset:256
	v_pk_mul_f32 v[116:117], v[116:117], v[248:249] op_sel:[0,1] op_sel_hi:[1,1]
	v_pk_mul_f32 v[118:119], v[118:119], v[248:249] op_sel:[0,1] op_sel_hi:[1,1]
	v_pk_mul_f32 v[108:109], v[108:109], v[248:249] op_sel:[0,1] op_sel_hi:[1,1]
	v_pk_mul_f32 v[110:111], v[110:111], v[248:249] op_sel:[0,1] op_sel_hi:[1,1]
	v_cvt_pk_bf16_f32 v116, v116, v117
	v_cvt_pk_bf16_f32 v117, v118, v119
	v_cvt_pk_bf16_f32 v118, v108, v109
	v_cvt_pk_bf16_f32 v119, v110, v111
	s_add_u32 s100, s84, 0x1a000
	s_addc_u32 s101, s85, 0
	global_store_dwordx4 v239, v[116:119], s[100:101]
	v_pk_mul_f32 v[96:97], v[96:97], v[248:249] op_sel:[0,1] op_sel_hi:[1,1]
	v_pk_mul_f32 v[98:99], v[98:99], v[248:249] op_sel:[0,1] op_sel_hi:[1,1]
	v_pk_mul_f32 v[88:89], v[88:89], v[248:249] op_sel:[0,1] op_sel_hi:[1,1]
	v_pk_mul_f32 v[90:91], v[90:91], v[248:249] op_sel:[0,1] op_sel_hi:[1,1]
	v_cvt_pk_bf16_f32 v96, v96, v97
	v_cvt_pk_bf16_f32 v97, v98, v99
	v_cvt_pk_bf16_f32 v98, v88, v89
	v_cvt_pk_bf16_f32 v99, v90, v91
	s_add_u32 s100, s84, 0x1a000
	s_addc_u32 s101, s85, 0
	global_store_dwordx4 v239, v[96:99], s[100:101] offset:256
	v_pk_mul_f32 v[100:101], v[100:101], v[250:251] op_sel_hi:[1,0]
	v_pk_mul_f32 v[102:103], v[102:103], v[250:251] op_sel_hi:[1,0]
	v_pk_mul_f32 v[92:93], v[92:93], v[250:251] op_sel_hi:[1,0]
	v_pk_mul_f32 v[94:95], v[94:95], v[250:251] op_sel_hi:[1,0]
	v_cvt_pk_bf16_f32 v100, v100, v101
	v_cvt_pk_bf16_f32 v101, v102, v103
	v_cvt_pk_bf16_f32 v102, v92, v93
	v_cvt_pk_bf16_f32 v103, v94, v95
	s_add_u32 s100, s84, 0x34000
	s_addc_u32 s101, s85, 0
	global_store_dwordx4 v239, v[100:103], s[100:101]
	v_pk_mul_f32 v[80:81], v[80:81], v[250:251] op_sel_hi:[1,0]
	v_pk_mul_f32 v[82:83], v[82:83], v[250:251] op_sel_hi:[1,0]
	v_pk_mul_f32 v[72:73], v[72:73], v[250:251] op_sel_hi:[1,0]
	v_pk_mul_f32 v[74:75], v[74:75], v[250:251] op_sel_hi:[1,0]
	v_cvt_pk_bf16_f32 v80, v80, v81
	v_cvt_pk_bf16_f32 v81, v82, v83
	v_cvt_pk_bf16_f32 v82, v72, v73
	v_cvt_pk_bf16_f32 v83, v74, v75
	s_add_u32 s100, s84, 0x34000
	s_addc_u32 s101, s85, 0
	global_store_dwordx4 v239, v[80:83], s[100:101] offset:256
	v_pk_mul_f32 v[84:85], v[84:85], v[250:251] op_sel:[0,1] op_sel_hi:[1,1]
	v_pk_mul_f32 v[86:87], v[86:87], v[250:251] op_sel:[0,1] op_sel_hi:[1,1]
	v_pk_mul_f32 v[76:77], v[76:77], v[250:251] op_sel:[0,1] op_sel_hi:[1,1]
	v_pk_mul_f32 v[78:79], v[78:79], v[250:251] op_sel:[0,1] op_sel_hi:[1,1]
	v_cvt_pk_bf16_f32 v84, v84, v85
	v_cvt_pk_bf16_f32 v85, v86, v87
	v_cvt_pk_bf16_f32 v86, v76, v77
	v_cvt_pk_bf16_f32 v87, v78, v79
	s_add_u32 s100, s84, 0x4e000
	s_addc_u32 s101, s85, 0
	global_store_dwordx4 v239, v[84:87], s[100:101]
	v_lshrrev_b32_e32 v144, 6, v204
	v_mul_u32_u24_e32 v144, 0xc00, v144
	v_and_b32_e32 v172, 63, v204
	v_lshl_add_u32 v144, v172, 4, v144
	v_add_u32_e32 v144, 0x21010, v144
	v_pk_mul_f32 v[60:61], v[60:61], v[252:253] op_sel_hi:[1,0]
	v_pk_mul_f32 v[62:63], v[62:63], v[252:253] op_sel_hi:[1,0]
	v_pk_mul_f32 v[56:57], v[56:57], v[252:253] op_sel_hi:[1,0]
	v_pk_mul_f32 v[58:59], v[58:59], v[252:253] op_sel_hi:[1,0]
	v_cvt_pk_bf16_f32 v60, v60, v61
	v_cvt_pk_bf16_f32 v61, v62, v63
	v_cvt_pk_bf16_f32 v62, v56, v57
	v_cvt_pk_bf16_f32 v63, v58, v59
	ds_write_b128 v144, v[60:63] offset:0
	v_pk_mul_f32 v[48:49], v[48:49], v[252:253] op_sel_hi:[1,0]
	v_pk_mul_f32 v[50:51], v[50:51], v[252:253] op_sel_hi:[1,0]
	v_pk_mul_f32 v[40:41], v[40:41], v[252:253] op_sel_hi:[1,0]
	v_pk_mul_f32 v[42:43], v[42:43], v[252:253] op_sel_hi:[1,0]
	v_cvt_pk_bf16_f32 v48, v48, v49
	v_cvt_pk_bf16_f32 v49, v50, v51
	v_cvt_pk_bf16_f32 v50, v40, v41
	v_cvt_pk_bf16_f32 v51, v42, v43
	ds_write_b128 v144, v[48:51] offset:1024
	v_pk_mul_f32 v[68:69], v[68:69], v[250:251] op_sel:[0,1] op_sel_hi:[1,1]
	v_pk_mul_f32 v[70:71], v[70:71], v[250:251] op_sel:[0,1] op_sel_hi:[1,1]
	v_pk_mul_f32 v[64:65], v[64:65], v[250:251] op_sel:[0,1] op_sel_hi:[1,1]
	v_pk_mul_f32 v[66:67], v[66:67], v[250:251] op_sel:[0,1] op_sel_hi:[1,1]
	v_cvt_pk_bf16_f32 v68, v68, v69
	v_cvt_pk_bf16_f32 v69, v70, v71
	v_cvt_pk_bf16_f32 v70, v64, v65
	v_cvt_pk_bf16_f32 v71, v66, v67
	ds_write_b128 v144, v[68:71] offset:2048
	v_pk_mul_f32 v[52:53], v[52:53], v[252:253] op_sel:[0,1] op_sel_hi:[1,1]
	v_pk_mul_f32 v[54:55], v[54:55], v[252:253] op_sel:[0,1] op_sel_hi:[1,1]
	v_pk_mul_f32 v[44:45], v[44:45], v[252:253] op_sel:[0,1] op_sel_hi:[1,1]
	v_pk_mul_f32 v[46:47], v[46:47], v[252:253] op_sel:[0,1] op_sel_hi:[1,1]
	v_cvt_pk_bf16_f32 v230, v52, v53
	v_cvt_pk_bf16_f32 v231, v54, v55
	v_cvt_pk_bf16_f32 v232, v44, v45
	v_cvt_pk_bf16_f32 v233, v46, v47
	v_pk_mul_f32 v[32:33], v[32:33], v[252:253] op_sel:[0,1] op_sel_hi:[1,1]
	v_pk_mul_f32 v[34:35], v[34:35], v[252:253] op_sel:[0,1] op_sel_hi:[1,1]
	v_pk_mul_f32 v[24:25], v[24:25], v[252:253] op_sel:[0,1] op_sel_hi:[1,1]
	v_pk_mul_f32 v[26:27], v[26:27], v[252:253] op_sel:[0,1] op_sel_hi:[1,1]
	v_cvt_pk_bf16_f32 v234, v32, v33
	v_cvt_pk_bf16_f32 v235, v34, v35
	v_cvt_pk_bf16_f32 v236, v24, v25
	v_cvt_pk_bf16_f32 v237, v26, v27
	v_pk_mul_f32 v[36:37], v[36:37], v[254:255] op_sel_hi:[1,0]
	v_pk_mul_f32 v[38:39], v[38:39], v[254:255] op_sel_hi:[1,0]
	v_pk_mul_f32 v[28:29], v[28:29], v[254:255] op_sel_hi:[1,0]
	v_pk_mul_f32 v[30:31], v[30:31], v[254:255] op_sel_hi:[1,0]
	v_cvt_pk_bf16_f32 v240, v36, v37
	v_cvt_pk_bf16_f32 v241, v38, v39
	v_cvt_pk_bf16_f32 v242, v28, v29
	v_cvt_pk_bf16_f32 v243, v30, v31
	v_pk_mul_f32 v[16:17], v[16:17], v[254:255] op_sel_hi:[1,0]
	v_pk_mul_f32 v[18:19], v[18:19], v[254:255] op_sel_hi:[1,0]
	v_pk_mul_f32 v[8:9], v[8:9], v[254:255] op_sel_hi:[1,0]
	v_pk_mul_f32 v[10:11], v[10:11], v[254:255] op_sel_hi:[1,0]
	v_cvt_pk_bf16_f32 v244, v16, v17
	v_cvt_pk_bf16_f32 v245, v18, v19
	v_cvt_pk_bf16_f32 v246, v8, v9
	v_cvt_pk_bf16_f32 v247, v10, v11
	v_pk_mul_f32 v[20:21], v[20:21], v[254:255] op_sel:[0,1] op_sel_hi:[1,1]
	v_pk_mul_f32 v[22:23], v[22:23], v[254:255] op_sel:[0,1] op_sel_hi:[1,1]
	v_pk_mul_f32 v[12:13], v[12:13], v[254:255] op_sel:[0,1] op_sel_hi:[1,1]
	v_pk_mul_f32 v[14:15], v[14:15], v[254:255] op_sel:[0,1] op_sel_hi:[1,1]
	v_cvt_pk_bf16_f32 v248, v20, v21
	v_cvt_pk_bf16_f32 v249, v22, v23
	v_cvt_pk_bf16_f32 v250, v12, v13
	v_cvt_pk_bf16_f32 v251, v14, v15
	v_pk_mul_f32 v[4:5], v[4:5], v[254:255] op_sel:[0,1] op_sel_hi:[1,1]
	v_pk_mul_f32 v[6:7], v[6:7], v[254:255] op_sel:[0,1] op_sel_hi:[1,1]
	v_pk_mul_f32 v[0:1], v[0:1], v[254:255] op_sel:[0,1] op_sel_hi:[1,1]
	v_pk_mul_f32 v[2:3], v[2:3], v[254:255] op_sel:[0,1] op_sel_hi:[1,1]
	v_cvt_pk_bf16_f32 v252, v4, v5
	v_cvt_pk_bf16_f32 v253, v6, v7
	v_cvt_pk_bf16_f32 v254, v0, v1
	v_cvt_pk_bf16_f32 v255, v2, v3
	s_mov_b64 s[66:67], s[64:65]
	s_and_b64 vcc, exec, s[8:9]
	s_mov_b32 s73, s58
	s_mov_b64 s[12:13], s[62:63]
	s_mov_b32 s10, s60
	s_mov_b64 s[98:99], s[84:85]
	s_mov_b32 s32, 1
	s_cbranch_vccz .LBB0_1138
	s_add_u32 s100, s84, 0xea000
	s_addc_u32 s101, s85, 0
	global_store_dwordx4 v239, v[230:233], s[100:101]
	s_add_u32 s100, s84, 0xea000
	s_addc_u32 s101, s85, 0
	global_store_dwordx4 v239, v[234:237], s[100:101] offset:256
	s_add_u32 s100, s84, 0x104000
	s_addc_u32 s101, s85, 0
	global_store_dwordx4 v239, v[240:243], s[100:101]
	s_add_u32 s100, s84, 0x104000
	s_addc_u32 s101, s85, 0
	global_store_dwordx4 v239, v[244:247], s[100:101] offset:256
	s_add_u32 s100, s84, 0x11e000
	s_addc_u32 s101, s85, 0
	global_store_dwordx4 v239, v[248:251], s[100:101]
	s_add_u32 s100, s84, 0x11e000
	s_addc_u32 s101, s85, 0
	global_store_dwordx4 v239, v[252:255], s[100:101] offset:256
	s_nop 1
	v_lshrrev_b32_e32 v230, 6, v204
	v_mul_u32_u24_e32 v230, 0xc00, v230
	v_and_b32_e32 v231, 63, v204
	v_lshl_add_u32 v230, v231, 4, v230
	v_add_u32_e32 v230, 0x21010, v230
	ds_read_b128 v[230:233], v230 offset:0
	s_waitcnt lgkmcnt(0)
	s_add_u32 s100, s84, 0xd0000
	s_addc_u32 s101, s85, 0
	global_store_dwordx4 v239, v[230:233], s[100:101]
	v_lshrrev_b32_e32 v234, 6, v204
	v_mul_u32_u24_e32 v234, 0xc00, v234
	v_and_b32_e32 v235, 63, v204
	v_lshl_add_u32 v234, v235, 4, v234
	v_add_u32_e32 v234, 0x21010, v234
	ds_read_b128 v[234:237], v234 offset:1024
	s_waitcnt lgkmcnt(0)
	s_add_u32 s100, s84, 0xd0000
	s_addc_u32 s101, s85, 0
	global_store_dwordx4 v239, v[234:237], s[100:101] offset:256
	v_lshrrev_b32_e32 v248, 6, v204
	v_mul_u32_u24_e32 v248, 0xc00, v248
	v_and_b32_e32 v249, 63, v204
	v_lshl_add_u32 v248, v249, 4, v248
	v_add_u32_e32 v248, 0x21010, v248
	ds_read_b128 v[248:251], v248 offset:2048
	s_waitcnt lgkmcnt(0)
	s_add_u32 s100, s84, 0x4e000
	s_addc_u32 s101, s85, 0
	global_store_dwordx4 v239, v[248:251], s[100:101] offset:256
	s_waitcnt vmcnt(0)
	s_cmpk_gt_u32 s0, 0xff
	s_cbranch_scc1 .LBB0_1145
	s_barrier

.Lds_P16_a_st:
	s_cmp_eq_u32 s32, 0
	s_cbranch_scc1 .Lds_P16_a_done
	s_cmp_eq_u32 s66, 0
	s_cbranch_scc1 .Lds_P16_a_0
	s_cmp_eq_u32 s66, 2
	s_cbranch_scc1 .Lds_P16_a_1
	s_add_u32 s100, s98, 0x160000
	s_addc_u32 s101, s99, 0
	global_store_dwordx4 v239, v[248:251], s[100:101]
	v_lshrrev_b32_e32 v230, 6, v204
	v_mul_u32_u24_e32 v230, 0xc00, v230
	v_and_b32_e32 v231, 63, v204
	v_lshl_add_u32 v230, v231, 4, v230
	v_add_u32_e32 v230, 0x21010, v230
	ds_read_b128 v[230:233], v230 offset:0
	s_waitcnt lgkmcnt(0)
	s_add_u32 s100, s98, 0x100000
	s_addc_u32 s101, s99, 0
	global_store_dwordx4 v239, v[230:233], s[100:101]
	s_branch .Lds_P16_a_done

.Lds_P16_b_st:
	s_cmp_eq_u32 s32, 0
	s_cbranch_scc1 .Lds_P16_b_done
	s_cmp_eq_u32 s66, 0
	s_cbranch_scc1 .Lds_P16_b_0
	s_cmp_eq_u32 s66, 2
	s_cbranch_scc1 .Lds_P16_b_1
	s_add_u32 s100, s98, 0x160000
	s_addc_u32 s101, s99, 0
	global_store_dwordx4 v239, v[252:255], s[100:101] offset:256
	v_lshrrev_b32_e32 v234, 6, v204
	v_mul_u32_u24_e32 v234, 0xc00, v234
	v_and_b32_e32 v235, 63, v204
	v_lshl_add_u32 v234, v235, 4, v234
	v_add_u32_e32 v234, 0x21010, v234
	ds_read_b128 v[234:237], v234 offset:1024
	s_waitcnt lgkmcnt(0)
	s_add_u32 s100, s98, 0x100000
	s_addc_u32 s101, s99, 0
	global_store_dwordx4 v239, v[234:237], s[100:101] offset:256
	s_branch .Lds_P16_b_done

.Lepi_P16_start:
	s_mul_i32 s82, s8, 0x200000
	s_lshl_b32 s84, s62, 9
	s_add_u32 s82, s82, s84
	s_add_u32 s84, s14, s82
	s_addc_u32 s85, s15, 0
	v_pk_mul_f32 v[124:125], v[124:125], v[248:249] op_sel_hi:[1,0]
	v_pk_mul_f32 v[126:127], v[126:127], v[248:249] op_sel_hi:[1,0]
	v_pk_mul_f32 v[120:121], v[120:121], v[248:249] op_sel_hi:[1,0]
	v_pk_mul_f32 v[122:123], v[122:123], v[248:249] op_sel_hi:[1,0]
	v_max_f32_e32 v124, 0, v124
	v_max_f32_e32 v125, 0, v125
	v_max_f32_e32 v126, 0, v126
	v_max_f32_e32 v127, 0, v127
	v_max_f32_e32 v120, 0, v120
	v_max_f32_e32 v121, 0, v121
	v_max_f32_e32 v122, 0, v122
	v_max_f32_e32 v123, 0, v123
	v_pk_mul_f32 v[124:125], v[124:125], v[124:125]
	v_pk_mul_f32 v[126:127], v[126:127], v[126:127]
	v_pk_mul_f32 v[120:121], v[120:121], v[120:121]
	v_pk_mul_f32 v[122:123], v[122:123], v[122:123]
	v_cvt_pk_bf16_f32 v124, v124, v125
	v_cvt_pk_bf16_f32 v125, v126, v127
	v_cvt_pk_bf16_f32 v126, v120, v121
	v_cvt_pk_bf16_f32 v127, v122, v123
	global_store_dwordx4 v239, v[124:127], s[84:85]
	v_pk_mul_f32 v[116:117], v[116:117], v[248:249] op_sel_hi:[1,0]
	v_pk_mul_f32 v[118:119], v[118:119], v[248:249] op_sel_hi:[1,0]
	v_pk_mul_f32 v[112:113], v[112:113], v[248:249] op_sel_hi:[1,0]
	v_pk_mul_f32 v[114:115], v[114:115], v[248:249] op_sel_hi:[1,0]
	v_max_f32_e32 v116, 0, v116
	v_max_f32_e32 v117, 0, v117
	v_max_f32_e32 v118, 0, v118
	v_max_f32_e32 v119, 0, v119
	v_max_f32_e32 v112, 0, v112
	v_max_f32_e32 v113, 0, v113
	v_max_f32_e32 v114, 0, v114
	v_max_f32_e32 v115, 0, v115
	v_pk_mul_f32 v[116:117], v[116:117], v[116:117]
	v_pk_mul_f32 v[118:119], v[118:119], v[118:119]
	v_pk_mul_f32 v[112:113], v[112:113], v[112:113]
	v_pk_mul_f32 v[114:115], v[114:115], v[114:115]
	v_cvt_pk_bf16_f32 v116, v116, v117
	v_cvt_pk_bf16_f32 v117, v118, v119
	v_cvt_pk_bf16_f32 v118, v112, v113
	v_cvt_pk_bf16_f32 v119, v114, v115
	global_store_dwordx4 v239, v[116:119], s[84:85] offset:256
	v_pk_mul_f32 v[108:109], v[108:109], v[248:249] op_sel:[0,1] op_sel_hi:[1,1]
	v_pk_mul_f32 v[110:111], v[110:111], v[248:249] op_sel:[0,1] op_sel_hi:[1,1]
	v_pk_mul_f32 v[104:105], v[104:105], v[248:249] op_sel:[0,1] op_sel_hi:[1,1]
	v_pk_mul_f32 v[106:107], v[106:107], v[248:249] op_sel:[0,1] op_sel_hi:[1,1]
	v_max_f32_e32 v108, 0, v108
	v_max_f32_e32 v109, 0, v109
	v_max_f32_e32 v110, 0, v110
	v_max_f32_e32 v111, 0, v111
	v_max_f32_e32 v104, 0, v104
	v_max_f32_e32 v105, 0, v105
	v_max_f32_e32 v106, 0, v106
	v_max_f32_e32 v107, 0, v107
	v_pk_mul_f32 v[108:109], v[108:109], v[108:109]
	v_pk_mul_f32 v[110:111], v[110:111], v[110:111]
	v_pk_mul_f32 v[104:105], v[104:105], v[104:105]
	v_pk_mul_f32 v[106:107], v[106:107], v[106:107]
	v_cvt_pk_bf16_f32 v108, v108, v109
	v_cvt_pk_bf16_f32 v109, v110, v111
	v_cvt_pk_bf16_f32 v110, v104, v105
	v_cvt_pk_bf16_f32 v111, v106, v107
	s_add_u32 s100, s84, 0x20000
	s_addc_u32 s101, s85, 0
	global_store_dwordx4 v239, v[108:111], s[100:101]
	v_pk_mul_f32 v[100:101], v[100:101], v[248:249] op_sel:[0,1] op_sel_hi:[1,1]
	v_pk_mul_f32 v[102:103], v[102:103], v[248:249] op_sel:[0,1] op_sel_hi:[1,1]
	v_pk_mul_f32 v[96:97], v[96:97], v[248:249] op_sel:[0,1] op_sel_hi:[1,1]
	v_pk_mul_f32 v[98:99], v[98:99], v[248:249] op_sel:[0,1] op_sel_hi:[1,1]
	v_max_f32_e32 v100, 0, v100
	v_max_f32_e32 v101, 0, v101
	v_max_f32_e32 v102, 0, v102
	v_max_f32_e32 v103, 0, v103
	v_max_f32_e32 v96, 0, v96
	v_max_f32_e32 v97, 0, v97
	v_max_f32_e32 v98, 0, v98
	v_max_f32_e32 v99, 0, v99
	v_pk_mul_f32 v[100:101], v[100:101], v[100:101]
	v_pk_mul_f32 v[102:103], v[102:103], v[102:103]
	v_pk_mul_f32 v[96:97], v[96:97], v[96:97]
	v_pk_mul_f32 v[98:99], v[98:99], v[98:99]
	v_cvt_pk_bf16_f32 v100, v100, v101
	v_cvt_pk_bf16_f32 v101, v102, v103
	v_cvt_pk_bf16_f32 v102, v96, v97
	v_cvt_pk_bf16_f32 v103, v98, v99
	s_add_u32 s100, s84, 0x20000
	s_addc_u32 s101, s85, 0
	global_store_dwordx4 v239, v[100:103], s[100:101] offset:256
	v_pk_mul_f32 v[92:93], v[92:93], v[250:251] op_sel_hi:[1,0]
	v_pk_mul_f32 v[94:95], v[94:95], v[250:251] op_sel_hi:[1,0]
	v_pk_mul_f32 v[88:89], v[88:89], v[250:251] op_sel_hi:[1,0]
	v_pk_mul_f32 v[90:91], v[90:91], v[250:251] op_sel_hi:[1,0]
	v_max_f32_e32 v92, 0, v92
	v_max_f32_e32 v93, 0, v93
	v_max_f32_e32 v94, 0, v94
	v_max_f32_e32 v95, 0, v95
	v_max_f32_e32 v88, 0, v88
	v_max_f32_e32 v89, 0, v89
	v_max_f32_e32 v90, 0, v90
	v_max_f32_e32 v91, 0, v91
	v_pk_mul_f32 v[92:93], v[92:93], v[92:93]
	v_pk_mul_f32 v[94:95], v[94:95], v[94:95]
	v_pk_mul_f32 v[88:89], v[88:89], v[88:89]
	v_pk_mul_f32 v[90:91], v[90:91], v[90:91]
	v_cvt_pk_bf16_f32 v92, v92, v93
	v_cvt_pk_bf16_f32 v93, v94, v95
	v_cvt_pk_bf16_f32 v94, v88, v89
	v_cvt_pk_bf16_f32 v95, v90, v91
	s_add_u32 s100, s84, 0x40000
	s_addc_u32 s101, s85, 0
	global_store_dwordx4 v239, v[92:95], s[100:101]
	v_pk_mul_f32 v[84:85], v[84:85], v[250:251] op_sel_hi:[1,0]
	v_pk_mul_f32 v[86:87], v[86:87], v[250:251] op_sel_hi:[1,0]
	v_pk_mul_f32 v[80:81], v[80:81], v[250:251] op_sel_hi:[1,0]
	v_pk_mul_f32 v[82:83], v[82:83], v[250:251] op_sel_hi:[1,0]
	v_max_f32_e32 v84, 0, v84
	v_max_f32_e32 v85, 0, v85
	v_max_f32_e32 v86, 0, v86
	v_max_f32_e32 v87, 0, v87
	v_max_f32_e32 v80, 0, v80
	v_max_f32_e32 v81, 0, v81
	v_max_f32_e32 v82, 0, v82
	v_max_f32_e32 v83, 0, v83
	v_pk_mul_f32 v[84:85], v[84:85], v[84:85]
	v_pk_mul_f32 v[86:87], v[86:87], v[86:87]
	v_pk_mul_f32 v[80:81], v[80:81], v[80:81]
	v_pk_mul_f32 v[82:83], v[82:83], v[82:83]
	v_cvt_pk_bf16_f32 v84, v84, v85
	v_cvt_pk_bf16_f32 v85, v86, v87
	v_cvt_pk_bf16_f32 v86, v80, v81
	v_cvt_pk_bf16_f32 v87, v82, v83
	s_add_u32 s100, s84, 0x40000
	s_addc_u32 s101, s85, 0
	global_store_dwordx4 v239, v[84:87], s[100:101] offset:256
	v_pk_mul_f32 v[76:77], v[76:77], v[250:251] op_sel:[0,1] op_sel_hi:[1,1]
	v_pk_mul_f32 v[78:79], v[78:79], v[250:251] op_sel:[0,1] op_sel_hi:[1,1]
	v_pk_mul_f32 v[72:73], v[72:73], v[250:251] op_sel:[0,1] op_sel_hi:[1,1]
	v_pk_mul_f32 v[74:75], v[74:75], v[250:251] op_sel:[0,1] op_sel_hi:[1,1]
	v_max_f32_e32 v76, 0, v76
	v_max_f32_e32 v77, 0, v77
	v_max_f32_e32 v78, 0, v78
	v_max_f32_e32 v79, 0, v79
	v_max_f32_e32 v72, 0, v72
	v_max_f32_e32 v73, 0, v73
	v_max_f32_e32 v74, 0, v74
	v_max_f32_e32 v75, 0, v75
	v_pk_mul_f32 v[76:77], v[76:77], v[76:77]
	v_pk_mul_f32 v[78:79], v[78:79], v[78:79]
	v_pk_mul_f32 v[72:73], v[72:73], v[72:73]
	v_pk_mul_f32 v[74:75], v[74:75], v[74:75]
	v_cvt_pk_bf16_f32 v76, v76, v77
	v_cvt_pk_bf16_f32 v77, v78, v79
	v_cvt_pk_bf16_f32 v78, v72, v73
	v_cvt_pk_bf16_f32 v79, v74, v75
	s_add_u32 s100, s84, 0x60000
	s_addc_u32 s101, s85, 0
	global_store_dwordx4 v239, v[76:79], s[100:101]
	v_lshrrev_b32_e32 v144, 6, v204
	v_mul_u32_u24_e32 v144, 0xc00, v144
	v_and_b32_e32 v172, 63, v204
	v_lshl_add_u32 v144, v172, 4, v144
	v_add_u32_e32 v144, 0x21010, v144
	v_pk_mul_f32 v[60:61], v[60:61], v[252:253] op_sel_hi:[1,0]
	v_pk_mul_f32 v[62:63], v[62:63], v[252:253] op_sel_hi:[1,0]
	v_pk_mul_f32 v[56:57], v[56:57], v[252:253] op_sel_hi:[1,0]
	v_pk_mul_f32 v[58:59], v[58:59], v[252:253] op_sel_hi:[1,0]
	v_max_f32_e32 v60, 0, v60
	v_max_f32_e32 v61, 0, v61
	v_max_f32_e32 v62, 0, v62
	v_max_f32_e32 v63, 0, v63
	v_max_f32_e32 v56, 0, v56
	v_max_f32_e32 v57, 0, v57
	v_max_f32_e32 v58, 0, v58
	v_max_f32_e32 v59, 0, v59
	v_pk_mul_f32 v[60:61], v[60:61], v[60:61]
	v_pk_mul_f32 v[62:63], v[62:63], v[62:63]
	v_pk_mul_f32 v[56:57], v[56:57], v[56:57]
	v_pk_mul_f32 v[58:59], v[58:59], v[58:59]
	v_cvt_pk_bf16_f32 v60, v60, v61
	v_cvt_pk_bf16_f32 v61, v62, v63
	v_cvt_pk_bf16_f32 v62, v56, v57
	v_cvt_pk_bf16_f32 v63, v58, v59
	ds_write_b128 v144, v[60:63] offset:0
	v_pk_mul_f32 v[52:53], v[52:53], v[252:253] op_sel_hi:[1,0]
	v_pk_mul_f32 v[54:55], v[54:55], v[252:253] op_sel_hi:[1,0]
	v_pk_mul_f32 v[48:49], v[48:49], v[252:253] op_sel_hi:[1,0]
	v_pk_mul_f32 v[50:51], v[50:51], v[252:253] op_sel_hi:[1,0]
	v_max_f32_e32 v52, 0, v52
	v_max_f32_e32 v53, 0, v53
	v_max_f32_e32 v54, 0, v54
	v_max_f32_e32 v55, 0, v55
	v_max_f32_e32 v48, 0, v48
	v_max_f32_e32 v49, 0, v49
	v_max_f32_e32 v50, 0, v50
	v_max_f32_e32 v51, 0, v51
	v_pk_mul_f32 v[52:53], v[52:53], v[52:53]
	v_pk_mul_f32 v[54:55], v[54:55], v[54:55]
	v_pk_mul_f32 v[48:49], v[48:49], v[48:49]
	v_pk_mul_f32 v[50:51], v[50:51], v[50:51]
	v_cvt_pk_bf16_f32 v52, v52, v53
	v_cvt_pk_bf16_f32 v53, v54, v55
	v_cvt_pk_bf16_f32 v54, v48, v49
	v_cvt_pk_bf16_f32 v55, v50, v51
	ds_write_b128 v144, v[52:55] offset:1024
	v_pk_mul_f32 v[68:69], v[68:69], v[250:251] op_sel:[0,1] op_sel_hi:[1,1]
	v_pk_mul_f32 v[70:71], v[70:71], v[250:251] op_sel:[0,1] op_sel_hi:[1,1]
	v_pk_mul_f32 v[64:65], v[64:65], v[250:251] op_sel:[0,1] op_sel_hi:[1,1]
	v_pk_mul_f32 v[66:67], v[66:67], v[250:251] op_sel:[0,1] op_sel_hi:[1,1]
	v_max_f32_e32 v68, 0, v68
	v_max_f32_e32 v69, 0, v69
	v_max_f32_e32 v70, 0, v70
	v_max_f32_e32 v71, 0, v71
	v_max_f32_e32 v64, 0, v64
	v_max_f32_e32 v65, 0, v65
	v_max_f32_e32 v66, 0, v66
	v_max_f32_e32 v67, 0, v67
	v_pk_mul_f32 v[68:69], v[68:69], v[68:69]
	v_pk_mul_f32 v[70:71], v[70:71], v[70:71]
	v_pk_mul_f32 v[64:65], v[64:65], v[64:65]
	v_pk_mul_f32 v[66:67], v[66:67], v[66:67]
	v_cvt_pk_bf16_f32 v68, v68, v69
	v_cvt_pk_bf16_f32 v69, v70, v71
	v_cvt_pk_bf16_f32 v70, v64, v65
	v_cvt_pk_bf16_f32 v71, v66, v67
	ds_write_b128 v144, v[68:71] offset:2048
	v_pk_mul_f32 v[44:45], v[44:45], v[252:253] op_sel:[0,1] op_sel_hi:[1,1]
	v_pk_mul_f32 v[46:47], v[46:47], v[252:253] op_sel:[0,1] op_sel_hi:[1,1]
	v_pk_mul_f32 v[40:41], v[40:41], v[252:253] op_sel:[0,1] op_sel_hi:[1,1]
	v_pk_mul_f32 v[42:43], v[42:43], v[252:253] op_sel:[0,1] op_sel_hi:[1,1]
	v_max_f32_e32 v44, 0, v44
	v_max_f32_e32 v45, 0, v45
	v_max_f32_e32 v46, 0, v46
	v_max_f32_e32 v47, 0, v47
	v_max_f32_e32 v40, 0, v40
	v_max_f32_e32 v41, 0, v41
	v_max_f32_e32 v42, 0, v42
	v_max_f32_e32 v43, 0, v43
	v_pk_mul_f32 v[44:45], v[44:45], v[44:45]
	v_pk_mul_f32 v[46:47], v[46:47], v[46:47]
	v_pk_mul_f32 v[40:41], v[40:41], v[40:41]
	v_pk_mul_f32 v[42:43], v[42:43], v[42:43]
	v_cvt_pk_bf16_f32 v230, v44, v45
	v_cvt_pk_bf16_f32 v231, v46, v47
	v_cvt_pk_bf16_f32 v232, v40, v41
	v_cvt_pk_bf16_f32 v233, v42, v43
	v_pk_mul_f32 v[36:37], v[36:37], v[252:253] op_sel:[0,1] op_sel_hi:[1,1]
	v_pk_mul_f32 v[38:39], v[38:39], v[252:253] op_sel:[0,1] op_sel_hi:[1,1]
	v_pk_mul_f32 v[32:33], v[32:33], v[252:253] op_sel:[0,1] op_sel_hi:[1,1]
	v_pk_mul_f32 v[34:35], v[34:35], v[252:253] op_sel:[0,1] op_sel_hi:[1,1]
	v_max_f32_e32 v36, 0, v36
	v_max_f32_e32 v37, 0, v37
	v_max_f32_e32 v38, 0, v38
	v_max_f32_e32 v39, 0, v39
	v_max_f32_e32 v32, 0, v32
	v_max_f32_e32 v33, 0, v33
	v_max_f32_e32 v34, 0, v34
	v_max_f32_e32 v35, 0, v35
	v_pk_mul_f32 v[36:37], v[36:37], v[36:37]
	v_pk_mul_f32 v[38:39], v[38:39], v[38:39]
	v_pk_mul_f32 v[32:33], v[32:33], v[32:33]
	v_pk_mul_f32 v[34:35], v[34:35], v[34:35]
	v_cvt_pk_bf16_f32 v234, v36, v37
	v_cvt_pk_bf16_f32 v235, v38, v39
	v_cvt_pk_bf16_f32 v236, v32, v33
	v_cvt_pk_bf16_f32 v237, v34, v35
	v_pk_mul_f32 v[28:29], v[28:29], v[254:255] op_sel_hi:[1,0]
	v_pk_mul_f32 v[30:31], v[30:31], v[254:255] op_sel_hi:[1,0]
	v_pk_mul_f32 v[24:25], v[24:25], v[254:255] op_sel_hi:[1,0]
	v_pk_mul_f32 v[26:27], v[26:27], v[254:255] op_sel_hi:[1,0]
	v_max_f32_e32 v28, 0, v28
	v_max_f32_e32 v29, 0, v29
	v_max_f32_e32 v30, 0, v30
	v_max_f32_e32 v31, 0, v31
	v_max_f32_e32 v24, 0, v24
	v_max_f32_e32 v25, 0, v25
	v_max_f32_e32 v26, 0, v26
	v_max_f32_e32 v27, 0, v27
	v_pk_mul_f32 v[28:29], v[28:29], v[28:29]
	v_pk_mul_f32 v[30:31], v[30:31], v[30:31]
	v_pk_mul_f32 v[24:25], v[24:25], v[24:25]
	v_pk_mul_f32 v[26:27], v[26:27], v[26:27]
	v_cvt_pk_bf16_f32 v240, v28, v29
	v_cvt_pk_bf16_f32 v241, v30, v31
	v_cvt_pk_bf16_f32 v242, v24, v25
	v_cvt_pk_bf16_f32 v243, v26, v27
	v_pk_mul_f32 v[20:21], v[20:21], v[254:255] op_sel_hi:[1,0]
	v_pk_mul_f32 v[22:23], v[22:23], v[254:255] op_sel_hi:[1,0]
	v_pk_mul_f32 v[16:17], v[16:17], v[254:255] op_sel_hi:[1,0]
	v_pk_mul_f32 v[18:19], v[18:19], v[254:255] op_sel_hi:[1,0]
	v_max_f32_e32 v20, 0, v20
	v_max_f32_e32 v21, 0, v21
	v_max_f32_e32 v22, 0, v22
	v_max_f32_e32 v23, 0, v23
	v_max_f32_e32 v16, 0, v16
	v_max_f32_e32 v17, 0, v17
	v_max_f32_e32 v18, 0, v18
	v_max_f32_e32 v19, 0, v19
	v_pk_mul_f32 v[20:21], v[20:21], v[20:21]
	v_pk_mul_f32 v[22:23], v[22:23], v[22:23]
	v_pk_mul_f32 v[16:17], v[16:17], v[16:17]
	v_pk_mul_f32 v[18:19], v[18:19], v[18:19]
	v_cvt_pk_bf16_f32 v244, v20, v21
	v_cvt_pk_bf16_f32 v245, v22, v23
	v_cvt_pk_bf16_f32 v246, v16, v17
	v_cvt_pk_bf16_f32 v247, v18, v19
	v_pk_mul_f32 v[12:13], v[12:13], v[254:255] op_sel:[0,1] op_sel_hi:[1,1]
	v_pk_mul_f32 v[14:15], v[14:15], v[254:255] op_sel:[0,1] op_sel_hi:[1,1]
	v_pk_mul_f32 v[8:9], v[8:9], v[254:255] op_sel:[0,1] op_sel_hi:[1,1]
	v_pk_mul_f32 v[10:11], v[10:11], v[254:255] op_sel:[0,1] op_sel_hi:[1,1]
	v_max_f32_e32 v12, 0, v12
	v_max_f32_e32 v13, 0, v13
	v_max_f32_e32 v14, 0, v14
	v_max_f32_e32 v15, 0, v15
	v_max_f32_e32 v8, 0, v8
	v_max_f32_e32 v9, 0, v9
	v_max_f32_e32 v10, 0, v10
	v_max_f32_e32 v11, 0, v11
	v_pk_mul_f32 v[12:13], v[12:13], v[12:13]
	v_pk_mul_f32 v[14:15], v[14:15], v[14:15]
	v_pk_mul_f32 v[8:9], v[8:9], v[8:9]
	v_pk_mul_f32 v[10:11], v[10:11], v[10:11]
	v_cvt_pk_bf16_f32 v248, v12, v13
	v_cvt_pk_bf16_f32 v249, v14, v15
	v_cvt_pk_bf16_f32 v250, v8, v9
	v_cvt_pk_bf16_f32 v251, v10, v11
	v_pk_mul_f32 v[4:5], v[4:5], v[254:255] op_sel:[0,1] op_sel_hi:[1,1]
	v_pk_mul_f32 v[6:7], v[6:7], v[254:255] op_sel:[0,1] op_sel_hi:[1,1]
	v_pk_mul_f32 v[0:1], v[0:1], v[254:255] op_sel:[0,1] op_sel_hi:[1,1]
	v_pk_mul_f32 v[2:3], v[2:3], v[254:255] op_sel:[0,1] op_sel_hi:[1,1]
	v_max_f32_e32 v4, 0, v4
	v_max_f32_e32 v5, 0, v5
	v_max_f32_e32 v6, 0, v6
	v_max_f32_e32 v7, 0, v7
	v_max_f32_e32 v0, 0, v0
	v_max_f32_e32 v1, 0, v1
	v_max_f32_e32 v2, 0, v2
	v_max_f32_e32 v3, 0, v3
	v_pk_mul_f32 v[4:5], v[4:5], v[4:5]
	v_pk_mul_f32 v[6:7], v[6:7], v[6:7]
	v_pk_mul_f32 v[0:1], v[0:1], v[0:1]
	v_pk_mul_f32 v[2:3], v[2:3], v[2:3]
	v_cvt_pk_bf16_f32 v252, v4, v5
	v_cvt_pk_bf16_f32 v253, v6, v7
	v_cvt_pk_bf16_f32 v254, v0, v1
	v_cvt_pk_bf16_f32 v255, v2, v3
	s_mov_b64 s[42:43], s[40:41]
	s_and_b64 vcc, exec, s[6:7]
	s_mov_b32 s62, s34
	s_mov_b32 s8, s36
	s_mov_b64 s[10:11], s[38:39]
	s_mov_b64 s[98:99], s[84:85]
	s_mov_b32 s32, 1
	s_cbranch_vccz .LBB0_1974
	s_add_u32 s100, s84, 0x120000
	s_addc_u32 s101, s85, 0
	global_store_dwordx4 v239, v[230:233], s[100:101]
	s_add_u32 s100, s84, 0x120000
	s_addc_u32 s101, s85, 0
	global_store_dwordx4 v239, v[234:237], s[100:101] offset:256
	s_add_u32 s100, s84, 0x140000
	s_addc_u32 s101, s85, 0
	global_store_dwordx4 v239, v[240:243], s[100:101]
	s_add_u32 s100, s84, 0x140000
	s_addc_u32 s101, s85, 0
	global_store_dwordx4 v239, v[244:247], s[100:101] offset:256
	s_add_u32 s100, s84, 0x160000
	s_addc_u32 s101, s85, 0
	global_store_dwordx4 v239, v[248:251], s[100:101]
	s_add_u32 s100, s84, 0x160000
	s_addc_u32 s101, s85, 0
	global_store_dwordx4 v239, v[252:255], s[100:101] offset:256
	s_nop 1
	v_lshrrev_b32_e32 v230, 6, v204
	v_mul_u32_u24_e32 v230, 0xc00, v230
	v_and_b32_e32 v231, 63, v204
	v_lshl_add_u32 v230, v231, 4, v230
	v_add_u32_e32 v230, 0x21010, v230
	ds_read_b128 v[230:233], v230 offset:0
	s_waitcnt lgkmcnt(0)
	s_add_u32 s100, s84, 0x100000
	s_addc_u32 s101, s85, 0
	global_store_dwordx4 v239, v[230:233], s[100:101]
	v_lshrrev_b32_e32 v234, 6, v204
	v_mul_u32_u24_e32 v234, 0xc00, v234
	v_and_b32_e32 v235, 63, v204
	v_lshl_add_u32 v234, v235, 4, v234
	v_add_u32_e32 v234, 0x21010, v234
	ds_read_b128 v[234:237], v234 offset:1024
	s_waitcnt lgkmcnt(0)
	s_add_u32 s100, s84, 0x100000
	s_addc_u32 s101, s85, 0
	global_store_dwordx4 v239, v[234:237], s[100:101] offset:256
	v_lshrrev_b32_e32 v248, 6, v204
	v_mul_u32_u24_e32 v248, 0xc00, v248
	v_and_b32_e32 v249, 63, v204
	v_lshl_add_u32 v248, v249, 4, v248
	v_add_u32_e32 v248, 0x21010, v248
	ds_read_b128 v[248:251], v248 offset:2048
	s_waitcnt lgkmcnt(0)
	s_add_u32 s100, s84, 0x60000
	s_addc_u32 s101, s85, 0
	global_store_dwordx4 v239, v[248:251], s[100:101] offset:256
	s_waitcnt vmcnt(0)
	s_cmpk_gt_u32 s0, 0xff
	s_cbranch_scc1 .LBB0_1985
	s_barrier

	.amdhsa_kernel _Z6k_mega6Params
		.amdhsa_group_segment_fixed_size 24576
		.amdhsa_private_segment_fixed_size 0
		.amdhsa_kernarg_size 448
		.amdhsa_user_sgpr_count 2
		.amdhsa_user_sgpr_dispatch_ptr 0
		.amdhsa_user_sgpr_queue_ptr 0
		.amdhsa_user_sgpr_kernarg_segment_ptr 1
		.amdhsa_user_sgpr_dispatch_id 0
		.amdhsa_user_sgpr_kernarg_preload_length 0
		.amdhsa_user_sgpr_kernarg_preload_offset 0
		.amdhsa_user_sgpr_private_segment_size 0
		.amdhsa_uses_dynamic_stack 0
		.amdhsa_enable_private_segment 0
		.amdhsa_system_sgpr_workgroup_id_x 1
		.amdhsa_system_sgpr_workgroup_id_y 0
		.amdhsa_system_sgpr_workgroup_id_z 0
		.amdhsa_system_sgpr_workgroup_info 0
		.amdhsa_system_vgpr_workitem_id 2
		.amdhsa_next_free_vgpr 256
		.amdhsa_next_free_sgpr 102
		.amdhsa_accum_offset 256
		.amdhsa_reserve_vcc 1
		.amdhsa_float_round_mode_32 0
		.amdhsa_float_round_mode_16_64 0
		.amdhsa_float_denorm_mode_32 3
		.amdhsa_float_denorm_mode_16_64 3
		.amdhsa_dx10_clamp 1
		.amdhsa_ieee_mode 1
		.amdhsa_fp16_overflow 0
		.amdhsa_tg_split 0
		.amdhsa_exception_fp_ieee_invalid_op 0
		.amdhsa_exception_fp_denorm_src 0
		.amdhsa_exception_fp_ieee_div_zero 0
		.amdhsa_exception_fp_ieee_overflow 0
		.amdhsa_exception_fp_ieee_underflow 0
		.amdhsa_exception_fp_ieee_inexact 0
		.amdhsa_exception_int_div_zero 0
	.end_amdhsa_kernel

amdhsa.kernels:
  - .agpr_count:     0
    .args:
      - .offset:         0
        .size:           192
        .value_kind:     by_value
      - .offset:         192
        .size:           4
        .value_kind:     hidden_block_count_x
      - .offset:         196
        .size:           4
        .value_kind:     hidden_block_count_y
      - .offset:         200
        .size:           4
        .value_kind:     hidden_block_count_z
      - .offset:         204
        .size:           2
        .value_kind:     hidden_group_size_x
      - .offset:         206
        .size:           2
        .value_kind:     hidden_group_size_y
      - .offset:         208
        .size:           2
        .value_kind:     hidden_group_size_z
      - .offset:         210
        .size:           2
        .value_kind:     hidden_remainder_x
      - .offset:         212
        .size:           2
        .value_kind:     hidden_remainder_y
      - .offset:         214
        .size:           2
        .value_kind:     hidden_remainder_z
      - .offset:         232
        .size:           8
        .value_kind:     hidden_global_offset_x
      - .offset:         240
        .size:           8
        .value_kind:     hidden_global_offset_y
      - .offset:         248
        .size:           8
        .value_kind:     hidden_global_offset_z
      - .offset:         256
        .size:           2
        .value_kind:     hidden_grid_dims
      - .offset:         280
        .size:           8
        .value_kind:     hidden_multigrid_sync_arg
      - .offset:         312
        .size:           4
        .value_kind:     hidden_dynamic_lds_size
    .group_segment_fixed_size: 24576
    .kernarg_segment_align: 8
    .kernarg_segment_size: 448
    .language:       OpenCL C
    .language_version:
      - 2
      - 0
    .max_flat_workgroup_size: 512
    .name:           _Z6k_mega6Params
    .private_segment_fixed_size: 0
    .sgpr_count:     108
    .sgpr_spill_count: 26
    .symbol:         _Z6k_mega6Params.kd
    .uniform_work_group_size: 1
    .uses_dynamic_stack: false
    .vgpr_count:     256
    .vgpr_spill_count: 0
    .wavefront_size: 64
